# combo1 + B-fragment LDS read addresses folded into one VGPR with immediates + merged load-segment waits
# baseline (speedup 1.0000x reference)
.LBB0_324:
	s_add_i32 vcc_lo, s66, 2
	s_add_u32 s34, s8, 0xfff00080
	s_addc_u32 s35, s9, -1
	s_add_i32 s89, 0, 0x10000
	s_cmp_eq_u32 s59, s66
	s_cselect_b32 s95, s65, s35
	s_cselect_b32 s94, s64, s34
	v_add_u32_e32 v0, s89, v217
	s_cselect_b32 s67, s53, s80
	s_cselect_b32 s66, s52, s70
	s_add_i32 vcc_hi, 0, 0x14000
	ds_read_b128 v[132:135], v0
	ds_read_b128 v[136:139], v0 offset:1024
	ds_read_b128 v[140:143], v0 offset:2048
	ds_read_b128 v[144:147], v0 offset:3072
	v_add_u32_e32 v0, vcc_hi, v217
	ds_read_b128 v[148:151], v0
	ds_read_b128 v[152:155], v0 offset:1024
	ds_read_b128 v[156:159], v0 offset:2048
	ds_read_b128 v[160:163], v0 offset:3072
	v_add_u32_e32 v0, 0, v216
	s_add_i32 m0, s29, 0xc000
	ds_read_b128 v[164:167], v0
	ds_read_b128 v[168:171], v0 offset:1024
	ds_read_b128 v[172:175], v0 offset:2048
	ds_read_b128 v[176:179], v0 offset:3072
	ds_read_b128 v[180:183], v0 offset:4096
	ds_read_b128 v[184:187], v0 offset:5120
	ds_read_b128 v[188:191], v0 offset:6144
	ds_read_b128 v[250:253], v0 offset:7168
	global_load_lds_dwordx4 v204, s[8:9]
	s_add_i32 m0, s29, 0xe000
	s_nop 0
	global_load_lds_dwordx4 v206, s[8:9]
	s_waitcnt vmcnt(8) lgkmcnt(0)
	s_barrier
	v_mfma_f32_16x16x32_bf16 v[128:131], v[132:135], v[164:167], v[128:131]
	v_mfma_f32_16x16x32_bf16 v[112:115], v[140:143], v[164:167], v[112:115]
	v_mfma_f32_16x16x32_bf16 v[120:123], v[132:135], v[172:175], v[120:123]
	v_mfma_f32_16x16x32_bf16 v[96:99], v[140:143], v[172:175], v[96:99]
	v_mfma_f32_16x16x32_bf16 v[104:107], v[132:135], v[180:183], v[104:107]
	v_mfma_f32_16x16x32_bf16 v[88:91], v[140:143], v[180:183], v[88:91]
	v_mfma_f32_16x16x32_bf16 v[84:87], v[132:135], v[188:191], v[84:87]
	v_mfma_f32_16x16x32_bf16 v[72:75], v[140:143], v[188:191], v[72:75]
	v_mfma_f32_16x16x32_bf16 v[128:131], v[136:139], v[168:171], v[128:131]
	v_mfma_f32_16x16x32_bf16 v[112:115], v[144:147], v[168:171], v[112:115]
	v_mfma_f32_16x16x32_bf16 v[120:123], v[136:139], v[176:179], v[120:123]
	v_mfma_f32_16x16x32_bf16 v[96:99], v[144:147], v[176:179], v[96:99]
	v_mfma_f32_16x16x32_bf16 v[104:107], v[136:139], v[184:187], v[104:107]
	v_mfma_f32_16x16x32_bf16 v[88:91], v[144:147], v[184:187], v[88:91]
	v_mfma_f32_16x16x32_bf16 v[84:87], v[136:139], v[250:253], v[84:87]
	v_mfma_f32_16x16x32_bf16 v[72:75], v[144:147], v[250:253], v[72:75]
	v_mfma_f32_16x16x32_bf16 v[124:127], v[148:151], v[164:167], v[124:127]
	v_mfma_f32_16x16x32_bf16 v[108:111], v[156:159], v[164:167], v[108:111]
	v_mfma_f32_16x16x32_bf16 v[116:119], v[148:151], v[172:175], v[116:119]
	v_mfma_f32_16x16x32_bf16 v[92:95], v[156:159], v[172:175], v[92:95]
	v_mfma_f32_16x16x32_bf16 v[100:103], v[148:151], v[180:183], v[100:103]
	v_mfma_f32_16x16x32_bf16 v[80:83], v[156:159], v[180:183], v[80:83]
	v_mfma_f32_16x16x32_bf16 v[76:79], v[148:151], v[188:191], v[76:79]
	v_mfma_f32_16x16x32_bf16 v[68:71], v[156:159], v[188:191], v[68:71]
	v_mfma_f32_16x16x32_bf16 v[124:127], v[152:155], v[168:171], v[124:127]
	v_mfma_f32_16x16x32_bf16 v[108:111], v[160:163], v[168:171], v[108:111]
	v_mfma_f32_16x16x32_bf16 v[116:119], v[152:155], v[176:179], v[116:119]
	v_mfma_f32_16x16x32_bf16 v[92:95], v[160:163], v[176:179], v[92:95]
	v_mfma_f32_16x16x32_bf16 v[100:103], v[152:155], v[184:187], v[100:103]
	v_mfma_f32_16x16x32_bf16 v[80:83], v[160:163], v[184:187], v[80:83]
	v_mfma_f32_16x16x32_bf16 v[76:79], v[152:155], v[250:253], v[76:79]
	v_mfma_f32_16x16x32_bf16 v[68:71], v[160:163], v[250:253], v[68:71]
	s_barrier
	s_add_i32 s34, s89, s0
	s_mov_b32 m0, s34
	ds_read_b128 v[164:167], v0 offset:16384
	ds_read_b128 v[168:171], v0 offset:17408
	ds_read_b128 v[172:175], v0 offset:18432
	ds_read_b128 v[176:179], v0 offset:19456
	ds_read_b128 v[180:183], v0 offset:20480
	ds_read_b128 v[184:187], v0 offset:21504
	ds_read_b128 v[188:191], v0 offset:22528
	ds_read_b128 v[250:253], v0 offset:23552
	global_load_lds_dwordx4 v196, s[66:67]
	s_add_i32 m0, s34, 0x2000
	s_add_u32 s34, s66, 0x4000
	s_addc_u32 s35, s67, 0
	s_add_i32 s89, vcc_hi, s0
	global_load_lds_dwordx4 v200, s[66:67]
	s_mov_b32 m0, s89
	s_nop 0
	global_load_lds_dwordx4 v196, s[34:35]
	s_add_i32 m0, s89, 0x2000
	s_nop 0
	global_load_lds_dwordx4 v200, s[34:35]
	s_mov_b32 m0, s29
	s_nop 0
	global_load_lds_dwordx4 v198, s[94:95]
	s_mov_b32 m0, s45
	s_nop 0
	global_load_lds_dwordx4 v202, s[94:95]
	s_waitcnt vmcnt(8) lgkmcnt(0)
	s_barrier
	v_mfma_f32_16x16x32_bf16 v[64:67], v[132:135], v[164:167], v[64:67]
	v_mfma_f32_16x16x32_bf16 v[56:59], v[140:143], v[164:167], v[56:59]
	v_mfma_f32_16x16x32_bf16 v[48:51], v[132:135], v[172:175], v[48:51]
	v_mfma_f32_16x16x32_bf16 v[40:43], v[140:143], v[172:175], v[40:43]
	v_mfma_f32_16x16x32_bf16 v[30:33], v[132:135], v[180:183], v[30:33]
	v_mfma_f32_16x16x32_bf16 v[26:29], v[140:143], v[180:183], v[26:29]
	v_mfma_f32_16x16x32_bf16 v[14:17], v[132:135], v[188:191], v[14:17]
	v_mfma_f32_16x16x32_bf16 v[10:13], v[140:143], v[188:191], v[10:13]
	v_mfma_f32_16x16x32_bf16 v[64:67], v[136:139], v[168:171], v[64:67]
	v_mfma_f32_16x16x32_bf16 v[56:59], v[144:147], v[168:171], v[56:59]
	v_mfma_f32_16x16x32_bf16 v[48:51], v[136:139], v[176:179], v[48:51]
	v_mfma_f32_16x16x32_bf16 v[40:43], v[144:147], v[176:179], v[40:43]
	v_mfma_f32_16x16x32_bf16 v[30:33], v[136:139], v[184:187], v[30:33]
	v_mfma_f32_16x16x32_bf16 v[26:29], v[144:147], v[184:187], v[26:29]
	v_mfma_f32_16x16x32_bf16 v[14:17], v[136:139], v[250:253], v[14:17]
	v_mfma_f32_16x16x32_bf16 v[10:13], v[144:147], v[250:253], v[10:13]
	v_mfma_f32_16x16x32_bf16 v[60:63], v[148:151], v[164:167], v[60:63]
	v_mfma_f32_16x16x32_bf16 v[52:55], v[156:159], v[164:167], v[52:55]
	v_mfma_f32_16x16x32_bf16 v[44:47], v[148:151], v[172:175], v[44:47]
	v_mfma_f32_16x16x32_bf16 v[36:39], v[156:159], v[172:175], v[36:39]
	v_mfma_f32_16x16x32_bf16 v[22:25], v[148:151], v[180:183], v[22:25]
	v_mfma_f32_16x16x32_bf16 v[18:21], v[156:159], v[180:183], v[18:21]
	v_mfma_f32_16x16x32_bf16 v[6:9], v[148:151], v[188:191], v[6:9]
	v_mfma_f32_16x16x32_bf16 v[2:5], v[156:159], v[188:191], v[2:5]
	v_mfma_f32_16x16x32_bf16 v[60:63], v[152:155], v[168:171], v[60:63]
	v_mfma_f32_16x16x32_bf16 v[52:55], v[160:163], v[168:171], v[52:55]
	v_mfma_f32_16x16x32_bf16 v[44:47], v[152:155], v[176:179], v[44:47]
	v_mfma_f32_16x16x32_bf16 v[36:39], v[160:163], v[176:179], v[36:39]
	v_mfma_f32_16x16x32_bf16 v[22:25], v[152:155], v[184:187], v[22:25]
	v_mfma_f32_16x16x32_bf16 v[18:21], v[160:163], v[184:187], v[18:21]
	v_mfma_f32_16x16x32_bf16 v[6:9], v[152:155], v[250:253], v[6:9]
	v_mfma_f32_16x16x32_bf16 v[2:5], v[160:163], v[250:253], v[2:5]
	s_barrier
	s_add_i32 s89, 0, 0x18000
	s_add_i32 vcc_hi, 0, 0x1c000
	v_add_u32_e32 v144, s89, v217
	v_add_u32_e32 v160, vcc_hi, v217
	ds_read_b128 v[132:135], v144
	ds_read_b128 v[136:139], v144 offset:1024
	ds_read_b128 v[140:143], v144 offset:2048
	ds_read_b128 v[144:147], v144 offset:3072
	ds_read_b128 v[148:151], v160
	ds_read_b128 v[152:155], v160 offset:1024
	ds_read_b128 v[156:159], v160 offset:2048
	ds_read_b128 v[160:163], v160 offset:3072
	s_add_u32 s34, s94, 0x100000
	s_addc_u32 s35, s95, 0
	s_mov_b32 m0, s82
	ds_read_b128 v[164:167], v0 offset:32768
	ds_read_b128 v[168:171], v0 offset:33792
	ds_read_b128 v[172:175], v0 offset:34816
	ds_read_b128 v[176:179], v0 offset:35840
	ds_read_b128 v[180:183], v0 offset:36864
	ds_read_b128 v[184:187], v0 offset:37888
	ds_read_b128 v[188:191], v0 offset:38912
	ds_read_b128 v[250:253], v0 offset:39936
	global_load_lds_dwordx4 v198, s[34:35]
	s_mov_b32 m0, s90
	s_nop 0
	global_load_lds_dwordx4 v202, s[34:35]
	s_waitcnt vmcnt(8) lgkmcnt(0)
	s_barrier
	v_mfma_f32_16x16x32_bf16 v[128:131], v[132:135], v[164:167], v[128:131]
	v_mfma_f32_16x16x32_bf16 v[112:115], v[140:143], v[164:167], v[112:115]
	v_mfma_f32_16x16x32_bf16 v[120:123], v[132:135], v[172:175], v[120:123]
	v_mfma_f32_16x16x32_bf16 v[96:99], v[140:143], v[172:175], v[96:99]
	v_mfma_f32_16x16x32_bf16 v[104:107], v[132:135], v[180:183], v[104:107]
	v_mfma_f32_16x16x32_bf16 v[88:91], v[140:143], v[180:183], v[88:91]
	v_mfma_f32_16x16x32_bf16 v[84:87], v[132:135], v[188:191], v[84:87]
	v_mfma_f32_16x16x32_bf16 v[72:75], v[140:143], v[188:191], v[72:75]
	v_mfma_f32_16x16x32_bf16 v[128:131], v[136:139], v[168:171], v[128:131]
	v_mfma_f32_16x16x32_bf16 v[112:115], v[144:147], v[168:171], v[112:115]
	v_mfma_f32_16x16x32_bf16 v[120:123], v[136:139], v[176:179], v[120:123]
	v_mfma_f32_16x16x32_bf16 v[96:99], v[144:147], v[176:179], v[96:99]
	v_mfma_f32_16x16x32_bf16 v[104:107], v[136:139], v[184:187], v[104:107]
	v_mfma_f32_16x16x32_bf16 v[88:91], v[144:147], v[184:187], v[88:91]
	v_mfma_f32_16x16x32_bf16 v[84:87], v[136:139], v[250:253], v[84:87]
	v_mfma_f32_16x16x32_bf16 v[72:75], v[144:147], v[250:253], v[72:75]
	v_mfma_f32_16x16x32_bf16 v[124:127], v[148:151], v[164:167], v[124:127]
	v_mfma_f32_16x16x32_bf16 v[108:111], v[156:159], v[164:167], v[108:111]
	v_mfma_f32_16x16x32_bf16 v[116:119], v[148:151], v[172:175], v[116:119]
	v_mfma_f32_16x16x32_bf16 v[92:95], v[156:159], v[172:175], v[92:95]
	v_mfma_f32_16x16x32_bf16 v[100:103], v[148:151], v[180:183], v[100:103]
	v_mfma_f32_16x16x32_bf16 v[80:83], v[156:159], v[180:183], v[80:83]
	v_mfma_f32_16x16x32_bf16 v[76:79], v[148:151], v[188:191], v[76:79]
	v_mfma_f32_16x16x32_bf16 v[68:71], v[156:159], v[188:191], v[68:71]
	v_mfma_f32_16x16x32_bf16 v[124:127], v[152:155], v[168:171], v[124:127]
	v_mfma_f32_16x16x32_bf16 v[108:111], v[160:163], v[168:171], v[108:111]
	v_mfma_f32_16x16x32_bf16 v[116:119], v[152:155], v[176:179], v[116:119]
	v_mfma_f32_16x16x32_bf16 v[92:95], v[160:163], v[176:179], v[92:95]
	v_mfma_f32_16x16x32_bf16 v[100:103], v[152:155], v[184:187], v[100:103]
	v_mfma_f32_16x16x32_bf16 v[80:83], v[160:163], v[184:187], v[80:83]
	v_mfma_f32_16x16x32_bf16 v[76:79], v[152:155], v[250:253], v[76:79]
	v_mfma_f32_16x16x32_bf16 v[68:71], v[160:163], v[250:253], v[68:71]
	s_barrier
	s_add_u32 s34, s66, 0x8000
	s_addc_u32 s35, s67, 0
	s_add_i32 s89, s89, s0
	s_mov_b32 m0, s89
	ds_read_b128 v[164:167], v0 offset:49152
	ds_read_b128 v[168:171], v0 offset:50176
	ds_read_b128 v[172:175], v0 offset:51200
	ds_read_b128 v[176:179], v0 offset:52224
	ds_read_b128 v[180:183], v0 offset:53248
	ds_read_b128 v[184:187], v0 offset:54272
	ds_read_b128 v[188:191], v0 offset:55296
	ds_read_b128 v[250:253], v0 offset:56320
	global_load_lds_dwordx4 v196, s[34:35]
	s_add_i32 m0, s89, 0x2000
	v_lshl_add_u64 v[210:211], s[34:35], 0, v[200:201]
	s_add_u32 s34, s66, 0xc000
	s_addc_u32 s35, s67, 0
	s_add_i32 s66, vcc_hi, s0
	global_load_lds_dwordx4 v[210:211], off
	s_mov_b32 m0, s66
	s_nop 0
	global_load_lds_dwordx4 v196, s[34:35]
	s_add_i32 m0, s66, 0x2000
	s_nop 0
	global_load_lds_dwordx4 v200, s[34:35]
	s_mov_b32 m0, s91
	s_nop 0
	s_add_u32 s100, s94, s92
	s_addc_u32 s101, s95, s93
	global_load_lds_dwordx4 v198, s[100:101]
	s_mov_b32 m0, s30
	s_nop 0
	s_add_u32 s100, s94, s92
	s_addc_u32 s101, s95, s93
	global_load_lds_dwordx4 v202, s[100:101]
	s_waitcnt vmcnt(8) lgkmcnt(0)
	s_barrier
	v_mfma_f32_16x16x32_bf16 v[64:67], v[132:135], v[164:167], v[64:67]
	v_mfma_f32_16x16x32_bf16 v[56:59], v[140:143], v[164:167], v[56:59]
	v_mfma_f32_16x16x32_bf16 v[48:51], v[132:135], v[172:175], v[48:51]
	v_mfma_f32_16x16x32_bf16 v[40:43], v[140:143], v[172:175], v[40:43]
	v_mfma_f32_16x16x32_bf16 v[30:33], v[132:135], v[180:183], v[30:33]
	v_mfma_f32_16x16x32_bf16 v[26:29], v[140:143], v[180:183], v[26:29]
	v_mfma_f32_16x16x32_bf16 v[14:17], v[132:135], v[188:191], v[14:17]
	v_mfma_f32_16x16x32_bf16 v[10:13], v[140:143], v[188:191], v[10:13]
	v_mfma_f32_16x16x32_bf16 v[64:67], v[136:139], v[168:171], v[64:67]
	v_mfma_f32_16x16x32_bf16 v[56:59], v[144:147], v[168:171], v[56:59]
	v_mfma_f32_16x16x32_bf16 v[48:51], v[136:139], v[176:179], v[48:51]
	v_mfma_f32_16x16x32_bf16 v[40:43], v[144:147], v[176:179], v[40:43]
	v_mfma_f32_16x16x32_bf16 v[30:33], v[136:139], v[184:187], v[30:33]
	v_mfma_f32_16x16x32_bf16 v[26:29], v[144:147], v[184:187], v[26:29]
	v_mfma_f32_16x16x32_bf16 v[14:17], v[136:139], v[250:253], v[14:17]
	v_mfma_f32_16x16x32_bf16 v[10:13], v[144:147], v[250:253], v[10:13]
	v_mfma_f32_16x16x32_bf16 v[60:63], v[148:151], v[164:167], v[60:63]
	v_mfma_f32_16x16x32_bf16 v[52:55], v[156:159], v[164:167], v[52:55]
	v_mfma_f32_16x16x32_bf16 v[44:47], v[148:151], v[172:175], v[44:47]
	v_mfma_f32_16x16x32_bf16 v[36:39], v[156:159], v[172:175], v[36:39]
	v_mfma_f32_16x16x32_bf16 v[22:25], v[148:151], v[180:183], v[22:25]
	v_mfma_f32_16x16x32_bf16 v[18:21], v[156:159], v[180:183], v[18:21]
	v_mfma_f32_16x16x32_bf16 v[6:9], v[148:151], v[188:191], v[6:9]
	v_mfma_f32_16x16x32_bf16 v[2:5], v[156:159], v[188:191], v[2:5]
	v_mfma_f32_16x16x32_bf16 v[60:63], v[152:155], v[168:171], v[60:63]
	v_mfma_f32_16x16x32_bf16 v[52:55], v[160:163], v[168:171], v[52:55]
	v_mfma_f32_16x16x32_bf16 v[44:47], v[152:155], v[176:179], v[44:47]
	v_mfma_f32_16x16x32_bf16 v[36:39], v[160:163], v[176:179], v[36:39]
	v_mfma_f32_16x16x32_bf16 v[22:25], v[152:155], v[184:187], v[22:25]
	v_mfma_f32_16x16x32_bf16 v[18:21], v[160:163], v[184:187], v[18:21]
	v_mfma_f32_16x16x32_bf16 v[6:9], v[152:155], v[250:253], v[6:9]
	v_mfma_f32_16x16x32_bf16 v[2:5], v[160:163], v[250:253], v[2:5]
	s_barrier
	s_add_u32 s70, s70, 0x10000
	s_addc_u32 s80, s80, 0
	s_add_u32 s8, s8, 0x100
	s_addc_u32 s9, s9, 0
	s_cmp_lt_i32 vcc_lo, s58
	s_mov_b32 s66, vcc_lo
	s_cbranch_scc1 .LBB0_324
	v_mov_b32_e32 v252, v212
	s_branch .LBB0_235

.LBB0_327:
	s_add_i32 s70, s8, 2
	s_add_u32 s9, s6, 0xfff00080
	s_addc_u32 s10, s7, -1
	s_add_i32 s34, 0, 0x10000
	s_cmp_eq_u32 s59, s8
	s_cselect_b32 s11, s65, s10
	s_cselect_b32 s10, s64, s9
	v_add_u32_e32 v0, s34, v217
	s_cselect_b32 s9, s53, s67
	s_cselect_b32 s8, s52, s66
	s_add_i32 s35, 0, 0x14000
	ds_read_b128 v[132:135], v0
	ds_read_b128 v[136:139], v0 offset:1024
	ds_read_b128 v[140:143], v0 offset:2048
	ds_read_b128 v[144:147], v0 offset:3072
	v_add_u32_e32 v0, s35, v217
	ds_read_b128 v[148:151], v0
	ds_read_b128 v[152:155], v0 offset:1024
	ds_read_b128 v[156:159], v0 offset:2048
	ds_read_b128 v[160:163], v0 offset:3072
	v_add_u32_e32 v0, 0, v216
	s_add_i32 m0, s29, 0xc000
	ds_read_b128 v[164:167], v0
	ds_read_b128 v[168:171], v0 offset:1024
	ds_read_b128 v[172:175], v0 offset:2048
	ds_read_b128 v[176:179], v0 offset:3072
	ds_read_b128 v[180:183], v0 offset:4096
	ds_read_b128 v[184:187], v0 offset:5120
	ds_read_b128 v[188:191], v0 offset:6144
	ds_read_b128 v[250:253], v0 offset:7168
	global_load_lds_dwordx4 v204, s[6:7]
	s_add_i32 m0, s29, 0xe000
	s_nop 0
	global_load_lds_dwordx4 v206, s[6:7]
	s_waitcnt vmcnt(8) lgkmcnt(0)
	s_barrier
	v_mfma_i32_16x16x64_i8 v[128:131], v[132:135], v[164:167], v[128:131]
	v_mfma_i32_16x16x64_i8 v[112:115], v[140:143], v[164:167], v[112:115]
	v_mfma_i32_16x16x64_i8 v[120:123], v[132:135], v[172:175], v[120:123]
	v_mfma_i32_16x16x64_i8 v[96:99], v[140:143], v[172:175], v[96:99]
	v_mfma_i32_16x16x64_i8 v[104:107], v[132:135], v[180:183], v[104:107]
	v_mfma_i32_16x16x64_i8 v[88:91], v[140:143], v[180:183], v[88:91]
	v_mfma_i32_16x16x64_i8 v[84:87], v[132:135], v[188:191], v[84:87]
	v_mfma_i32_16x16x64_i8 v[72:75], v[140:143], v[188:191], v[72:75]
	v_mfma_i32_16x16x64_i8 v[128:131], v[136:139], v[168:171], v[128:131]
	v_mfma_i32_16x16x64_i8 v[112:115], v[144:147], v[168:171], v[112:115]
	v_mfma_i32_16x16x64_i8 v[120:123], v[136:139], v[176:179], v[120:123]
	v_mfma_i32_16x16x64_i8 v[96:99], v[144:147], v[176:179], v[96:99]
	v_mfma_i32_16x16x64_i8 v[104:107], v[136:139], v[184:187], v[104:107]
	v_mfma_i32_16x16x64_i8 v[88:91], v[144:147], v[184:187], v[88:91]
	v_mfma_i32_16x16x64_i8 v[84:87], v[136:139], v[250:253], v[84:87]
	v_mfma_i32_16x16x64_i8 v[72:75], v[144:147], v[250:253], v[72:75]
	v_mfma_i32_16x16x64_i8 v[124:127], v[148:151], v[164:167], v[124:127]
	v_mfma_i32_16x16x64_i8 v[108:111], v[156:159], v[164:167], v[108:111]
	v_mfma_i32_16x16x64_i8 v[116:119], v[148:151], v[172:175], v[116:119]
	v_mfma_i32_16x16x64_i8 v[92:95], v[156:159], v[172:175], v[92:95]
	v_mfma_i32_16x16x64_i8 v[100:103], v[148:151], v[180:183], v[100:103]
	v_mfma_i32_16x16x64_i8 v[80:83], v[156:159], v[180:183], v[80:83]
	v_mfma_i32_16x16x64_i8 v[76:79], v[148:151], v[188:191], v[76:79]
	v_mfma_i32_16x16x64_i8 v[68:71], v[156:159], v[188:191], v[68:71]
	v_mfma_i32_16x16x64_i8 v[124:127], v[152:155], v[168:171], v[124:127]
	v_mfma_i32_16x16x64_i8 v[108:111], v[160:163], v[168:171], v[108:111]
	v_mfma_i32_16x16x64_i8 v[116:119], v[152:155], v[176:179], v[116:119]
	v_mfma_i32_16x16x64_i8 v[92:95], v[160:163], v[176:179], v[92:95]
	v_mfma_i32_16x16x64_i8 v[100:103], v[152:155], v[184:187], v[100:103]
	v_mfma_i32_16x16x64_i8 v[80:83], v[160:163], v[184:187], v[80:83]
	v_mfma_i32_16x16x64_i8 v[76:79], v[152:155], v[250:253], v[76:79]
	v_mfma_i32_16x16x64_i8 v[68:71], v[160:163], v[250:253], v[68:71]
	s_barrier
	s_add_i32 s34, s34, s0
	s_mov_b32 m0, s34
	ds_read_b128 v[164:167], v0 offset:16384
	ds_read_b128 v[168:171], v0 offset:17408
	ds_read_b128 v[172:175], v0 offset:18432
	ds_read_b128 v[176:179], v0 offset:19456
	ds_read_b128 v[180:183], v0 offset:20480
	ds_read_b128 v[184:187], v0 offset:21504
	ds_read_b128 v[188:191], v0 offset:22528
	ds_read_b128 v[250:253], v0 offset:23552
	global_load_lds_dwordx4 v196, s[8:9]
	s_add_i32 m0, s34, 0x2000
	s_add_u32 s94, s8, 0x4000
	s_addc_u32 s95, s9, 0
	s_add_i32 s34, s35, s0
	global_load_lds_dwordx4 v200, s[8:9]
	s_mov_b32 m0, s34
	v_lshl_add_u64 v[194:195], s[10:11], 0, v[202:203]
	global_load_lds_dwordx4 v196, s[94:95]
	s_add_i32 m0, s34, 0x2000
	s_nop 0
	global_load_lds_dwordx4 v200, s[94:95]
	v_lshl_add_u64 v[192:193], s[10:11], 0, v[198:199]
	s_mov_b32 m0, s29
	s_nop 0
	global_load_lds_dwordx4 v198, s[10:11]
	s_mov_b32 m0, s45
	s_nop 0
	global_load_lds_dwordx4 v202, s[10:11]
	s_waitcnt vmcnt(8) lgkmcnt(0)
	s_barrier
	v_mfma_i32_16x16x64_i8 v[64:67], v[132:135], v[164:167], v[64:67]
	v_mfma_i32_16x16x64_i8 v[56:59], v[140:143], v[164:167], v[56:59]
	v_mfma_i32_16x16x64_i8 v[48:51], v[132:135], v[172:175], v[48:51]
	v_mfma_i32_16x16x64_i8 v[40:43], v[140:143], v[172:175], v[40:43]
	v_mfma_i32_16x16x64_i8 v[30:33], v[132:135], v[180:183], v[30:33]
	v_mfma_i32_16x16x64_i8 v[26:29], v[140:143], v[180:183], v[26:29]
	v_mfma_i32_16x16x64_i8 v[14:17], v[132:135], v[188:191], v[14:17]
	v_mfma_i32_16x16x64_i8 v[10:13], v[140:143], v[188:191], v[10:13]
	v_mfma_i32_16x16x64_i8 v[64:67], v[136:139], v[168:171], v[64:67]
	v_mfma_i32_16x16x64_i8 v[56:59], v[144:147], v[168:171], v[56:59]
	v_mfma_i32_16x16x64_i8 v[48:51], v[136:139], v[176:179], v[48:51]
	v_mfma_i32_16x16x64_i8 v[40:43], v[144:147], v[176:179], v[40:43]
	v_mfma_i32_16x16x64_i8 v[30:33], v[136:139], v[184:187], v[30:33]
	v_mfma_i32_16x16x64_i8 v[26:29], v[144:147], v[184:187], v[26:29]
	v_mfma_i32_16x16x64_i8 v[14:17], v[136:139], v[250:253], v[14:17]
	v_mfma_i32_16x16x64_i8 v[10:13], v[144:147], v[250:253], v[10:13]
	v_mfma_i32_16x16x64_i8 v[60:63], v[148:151], v[164:167], v[60:63]
	v_mfma_i32_16x16x64_i8 v[52:55], v[156:159], v[164:167], v[52:55]
	v_mfma_i32_16x16x64_i8 v[44:47], v[148:151], v[172:175], v[44:47]
	v_mfma_i32_16x16x64_i8 v[36:39], v[156:159], v[172:175], v[36:39]
	v_mfma_i32_16x16x64_i8 v[22:25], v[148:151], v[180:183], v[22:25]
	v_mfma_i32_16x16x64_i8 v[18:21], v[156:159], v[180:183], v[18:21]
	v_mfma_i32_16x16x64_i8 v[6:9], v[148:151], v[188:191], v[6:9]
	v_mfma_i32_16x16x64_i8 v[2:5], v[156:159], v[188:191], v[2:5]
	v_mfma_i32_16x16x64_i8 v[60:63], v[152:155], v[168:171], v[60:63]
	v_mfma_i32_16x16x64_i8 v[52:55], v[160:163], v[168:171], v[52:55]
	v_mfma_i32_16x16x64_i8 v[44:47], v[152:155], v[176:179], v[44:47]
	v_mfma_i32_16x16x64_i8 v[36:39], v[160:163], v[176:179], v[36:39]
	v_mfma_i32_16x16x64_i8 v[22:25], v[152:155], v[184:187], v[22:25]
	v_mfma_i32_16x16x64_i8 v[18:21], v[160:163], v[184:187], v[18:21]
	v_mfma_i32_16x16x64_i8 v[6:9], v[152:155], v[250:253], v[6:9]
	v_mfma_i32_16x16x64_i8 v[2:5], v[160:163], v[250:253], v[2:5]
	s_barrier
	s_add_i32 s34, 0, 0x18000
	s_add_i32 s35, 0, 0x1c000
	v_add_u32_e32 v144, s34, v217
	v_add_u32_e32 v160, s35, v217
	ds_read_b128 v[132:135], v144
	ds_read_b128 v[136:139], v144 offset:1024
	ds_read_b128 v[140:143], v144 offset:2048
	ds_read_b128 v[144:147], v144 offset:3072
	ds_read_b128 v[148:151], v160
	ds_read_b128 v[152:155], v160 offset:1024
	ds_read_b128 v[156:159], v160 offset:2048
	ds_read_b128 v[160:163], v160 offset:3072
	s_add_u32 s10, s10, 0x100000
	s_addc_u32 s11, s11, 0
	s_mov_b32 m0, s82
	ds_read_b128 v[164:167], v0 offset:32768
	ds_read_b128 v[168:171], v0 offset:33792
	ds_read_b128 v[172:175], v0 offset:34816
	ds_read_b128 v[176:179], v0 offset:35840
	ds_read_b128 v[180:183], v0 offset:36864
	ds_read_b128 v[184:187], v0 offset:37888
	ds_read_b128 v[188:191], v0 offset:38912
	ds_read_b128 v[250:253], v0 offset:39936
	global_load_lds_dwordx4 v198, s[10:11]
	s_mov_b32 m0, s90
	s_nop 0
	global_load_lds_dwordx4 v202, s[10:11]
	s_waitcnt vmcnt(8) lgkmcnt(0)
	s_barrier
	v_mfma_i32_16x16x64_i8 v[128:131], v[132:135], v[164:167], v[128:131]
	v_mfma_i32_16x16x64_i8 v[112:115], v[140:143], v[164:167], v[112:115]
	v_mfma_i32_16x16x64_i8 v[120:123], v[132:135], v[172:175], v[120:123]
	v_mfma_i32_16x16x64_i8 v[96:99], v[140:143], v[172:175], v[96:99]
	v_mfma_i32_16x16x64_i8 v[104:107], v[132:135], v[180:183], v[104:107]
	v_mfma_i32_16x16x64_i8 v[88:91], v[140:143], v[180:183], v[88:91]
	v_mfma_i32_16x16x64_i8 v[84:87], v[132:135], v[188:191], v[84:87]
	v_mfma_i32_16x16x64_i8 v[72:75], v[140:143], v[188:191], v[72:75]
	v_mfma_i32_16x16x64_i8 v[128:131], v[136:139], v[168:171], v[128:131]
	v_mfma_i32_16x16x64_i8 v[112:115], v[144:147], v[168:171], v[112:115]
	v_mfma_i32_16x16x64_i8 v[120:123], v[136:139], v[176:179], v[120:123]
	v_mfma_i32_16x16x64_i8 v[96:99], v[144:147], v[176:179], v[96:99]
	v_mfma_i32_16x16x64_i8 v[104:107], v[136:139], v[184:187], v[104:107]
	v_mfma_i32_16x16x64_i8 v[88:91], v[144:147], v[184:187], v[88:91]
	v_mfma_i32_16x16x64_i8 v[84:87], v[136:139], v[250:253], v[84:87]
	v_mfma_i32_16x16x64_i8 v[72:75], v[144:147], v[250:253], v[72:75]
	v_mfma_i32_16x16x64_i8 v[124:127], v[148:151], v[164:167], v[124:127]
	v_mfma_i32_16x16x64_i8 v[108:111], v[156:159], v[164:167], v[108:111]
	v_mfma_i32_16x16x64_i8 v[116:119], v[148:151], v[172:175], v[116:119]
	v_mfma_i32_16x16x64_i8 v[92:95], v[156:159], v[172:175], v[92:95]
	v_mfma_i32_16x16x64_i8 v[100:103], v[148:151], v[180:183], v[100:103]
	v_mfma_i32_16x16x64_i8 v[80:83], v[156:159], v[180:183], v[80:83]
	v_mfma_i32_16x16x64_i8 v[76:79], v[148:151], v[188:191], v[76:79]
	v_mfma_i32_16x16x64_i8 v[68:71], v[156:159], v[188:191], v[68:71]
	v_mfma_i32_16x16x64_i8 v[124:127], v[152:155], v[168:171], v[124:127]
	v_mfma_i32_16x16x64_i8 v[108:111], v[160:163], v[168:171], v[108:111]
	v_mfma_i32_16x16x64_i8 v[116:119], v[152:155], v[176:179], v[116:119]
	v_mfma_i32_16x16x64_i8 v[92:95], v[160:163], v[176:179], v[92:95]
	v_mfma_i32_16x16x64_i8 v[100:103], v[152:155], v[184:187], v[100:103]
	v_mfma_i32_16x16x64_i8 v[80:83], v[160:163], v[184:187], v[80:83]
	v_mfma_i32_16x16x64_i8 v[76:79], v[152:155], v[250:253], v[76:79]
	v_mfma_i32_16x16x64_i8 v[68:71], v[160:163], v[250:253], v[68:71]
	s_barrier
	s_add_u32 s10, s8, 0x8000
	s_addc_u32 s11, s9, 0
	s_add_i32 s34, s34, s0
	s_mov_b32 m0, s34
	ds_read_b128 v[164:167], v0 offset:49152
	ds_read_b128 v[168:171], v0 offset:50176
	ds_read_b128 v[172:175], v0 offset:51200
	ds_read_b128 v[176:179], v0 offset:52224
	ds_read_b128 v[180:183], v0 offset:53248
	ds_read_b128 v[184:187], v0 offset:54272
	ds_read_b128 v[188:191], v0 offset:55296
	ds_read_b128 v[250:253], v0 offset:56320
	global_load_lds_dwordx4 v196, s[10:11]
	s_add_i32 m0, s34, 0x2000
	s_add_u32 s8, s8, 0xc000
	v_lshl_add_u64 v[210:211], s[10:11], 0, v[200:201]
	s_addc_u32 s9, s9, 0
	s_add_i32 s10, s35, s0
	global_load_lds_dwordx4 v[210:211], off
	s_mov_b32 m0, s10
	v_lshl_add_u64 v[192:193], v[192:193], 0, s[92:93]
	global_load_lds_dwordx4 v196, s[8:9]
	s_add_i32 m0, s10, 0x2000
	s_nop 0
	global_load_lds_dwordx4 v200, s[8:9]
	s_mov_b32 m0, s91
	s_nop 0
	global_load_lds_dwordx4 v[192:193], off
	v_lshl_add_u64 v[192:193], v[194:195], 0, s[92:93]
	s_mov_b32 m0, s30
	s_nop 0
	global_load_lds_dwordx4 v[192:193], off
	s_waitcnt vmcnt(8) lgkmcnt(0)
	s_barrier
	v_mfma_i32_16x16x64_i8 v[64:67], v[132:135], v[164:167], v[64:67]
	v_mfma_i32_16x16x64_i8 v[56:59], v[140:143], v[164:167], v[56:59]
	v_mfma_i32_16x16x64_i8 v[48:51], v[132:135], v[172:175], v[48:51]
	v_mfma_i32_16x16x64_i8 v[40:43], v[140:143], v[172:175], v[40:43]
	v_mfma_i32_16x16x64_i8 v[30:33], v[132:135], v[180:183], v[30:33]
	v_mfma_i32_16x16x64_i8 v[26:29], v[140:143], v[180:183], v[26:29]
	v_mfma_i32_16x16x64_i8 v[14:17], v[132:135], v[188:191], v[14:17]
	v_mfma_i32_16x16x64_i8 v[10:13], v[140:143], v[188:191], v[10:13]
	v_mfma_i32_16x16x64_i8 v[64:67], v[136:139], v[168:171], v[64:67]
	v_mfma_i32_16x16x64_i8 v[56:59], v[144:147], v[168:171], v[56:59]
	v_mfma_i32_16x16x64_i8 v[48:51], v[136:139], v[176:179], v[48:51]
	v_mfma_i32_16x16x64_i8 v[40:43], v[144:147], v[176:179], v[40:43]
	v_mfma_i32_16x16x64_i8 v[30:33], v[136:139], v[184:187], v[30:33]
	v_mfma_i32_16x16x64_i8 v[26:29], v[144:147], v[184:187], v[26:29]
	v_mfma_i32_16x16x64_i8 v[14:17], v[136:139], v[250:253], v[14:17]
	v_mfma_i32_16x16x64_i8 v[10:13], v[144:147], v[250:253], v[10:13]
	v_mfma_i32_16x16x64_i8 v[60:63], v[148:151], v[164:167], v[60:63]
	v_mfma_i32_16x16x64_i8 v[52:55], v[156:159], v[164:167], v[52:55]
	v_mfma_i32_16x16x64_i8 v[44:47], v[148:151], v[172:175], v[44:47]
	v_mfma_i32_16x16x64_i8 v[36:39], v[156:159], v[172:175], v[36:39]
	v_mfma_i32_16x16x64_i8 v[22:25], v[148:151], v[180:183], v[22:25]
	v_mfma_i32_16x16x64_i8 v[18:21], v[156:159], v[180:183], v[18:21]
	v_mfma_i32_16x16x64_i8 v[6:9], v[148:151], v[188:191], v[6:9]
	v_mfma_i32_16x16x64_i8 v[2:5], v[156:159], v[188:191], v[2:5]
	v_mfma_i32_16x16x64_i8 v[60:63], v[152:155], v[168:171], v[60:63]
	v_mfma_i32_16x16x64_i8 v[52:55], v[160:163], v[168:171], v[52:55]
	v_mfma_i32_16x16x64_i8 v[44:47], v[152:155], v[176:179], v[44:47]
	v_mfma_i32_16x16x64_i8 v[36:39], v[160:163], v[176:179], v[36:39]
	v_mfma_i32_16x16x64_i8 v[22:25], v[152:155], v[184:187], v[22:25]
	v_mfma_i32_16x16x64_i8 v[18:21], v[160:163], v[184:187], v[18:21]
	v_mfma_i32_16x16x64_i8 v[6:9], v[152:155], v[250:253], v[6:9]
	v_mfma_i32_16x16x64_i8 v[2:5], v[160:163], v[250:253], v[2:5]
	s_barrier
	s_add_u32 s66, s66, 0x10000
	s_addc_u32 s67, s67, 0
	s_add_u32 s6, s6, 0x100
	s_addc_u32 s7, s7, 0
	s_cmp_ge_i32 s70, s58
	s_mov_b32 s8, s70
	s_cbranch_scc0 .LBB0_327
	v_mov_b32_e32 v252, v212
	v_cndmask_b32_e64 v0, 0, 1, s[46:47]
	v_cmp_ne_u32_e64 s[6:7], 1, v0
	s_andn2_b64 vcc, exec, s[46:47]
	s_cbranch_vccz .LBB0_236
	s_branch .LBB0_237

.LBB0_706:
	s_add_u32 s21, s52, 0x10000
	s_addc_u32 s59, s53, 0
	s_add_u32 s50, s50, 0x80080
	v_mov_b32_e32 v36, 0
	s_addc_u32 s51, s51, 0
	s_mov_b32 s60, -2
	v_mov_b32_e32 v37, v36
	v_mov_b32_e32 v38, v36
	v_mov_b32_e32 v39, v36
	v_mov_b32_e32 v40, v36
	v_mov_b32_e32 v41, v36
	v_mov_b32_e32 v42, v36
	v_mov_b32_e32 v43, v36
	v_mov_b32_e32 v48, v36
	v_mov_b32_e32 v49, v36
	v_mov_b32_e32 v50, v36
	v_mov_b32_e32 v51, v36
	v_mov_b32_e32 v56, v36
	v_mov_b32_e32 v57, v36
	v_mov_b32_e32 v58, v36
	v_mov_b32_e32 v59, v36
	v_mov_b32_e32 v64, v36
	v_mov_b32_e32 v65, v36
	v_mov_b32_e32 v66, v36
	v_mov_b32_e32 v67, v36
	v_mov_b32_e32 v72, v36
	v_mov_b32_e32 v73, v36
	v_mov_b32_e32 v74, v36
	v_mov_b32_e32 v75, v36
	v_mov_b32_e32 v80, v36
	v_mov_b32_e32 v81, v36
	v_mov_b32_e32 v82, v36
	v_mov_b32_e32 v83, v36
	v_mov_b32_e32 v88, v36
	v_mov_b32_e32 v89, v36
	v_mov_b32_e32 v90, v36
	v_mov_b32_e32 v91, v36
	v_mov_b32_e32 v44, v36
	v_mov_b32_e32 v45, v36
	v_mov_b32_e32 v46, v36
	v_mov_b32_e32 v47, v36
	v_mov_b32_e32 v52, v36
	v_mov_b32_e32 v53, v36
	v_mov_b32_e32 v54, v36
	v_mov_b32_e32 v55, v36
	v_mov_b32_e32 v60, v36
	v_mov_b32_e32 v61, v36
	v_mov_b32_e32 v62, v36
	v_mov_b32_e32 v63, v36
	v_mov_b32_e32 v68, v36
	v_mov_b32_e32 v69, v36
	v_mov_b32_e32 v70, v36
	v_mov_b32_e32 v71, v36
	v_mov_b32_e32 v76, v36
	v_mov_b32_e32 v77, v36
	v_mov_b32_e32 v78, v36
	v_mov_b32_e32 v79, v36
	v_mov_b32_e32 v84, v36
	v_mov_b32_e32 v85, v36
	v_mov_b32_e32 v86, v36
	v_mov_b32_e32 v87, v36
	v_mov_b32_e32 v92, v36
	v_mov_b32_e32 v93, v36
	v_mov_b32_e32 v94, v36
	v_mov_b32_e32 v95, v36
	v_mov_b32_e32 v96, v36
	v_mov_b32_e32 v97, v36
	v_mov_b32_e32 v98, v36
	v_mov_b32_e32 v99, v36
	v_mov_b32_e32 v100, v36
	v_mov_b32_e32 v101, v36
	v_mov_b32_e32 v102, v36
	v_mov_b32_e32 v103, v36
	v_mov_b32_e32 v104, v36
	v_mov_b32_e32 v105, v36
	v_mov_b32_e32 v106, v36
	v_mov_b32_e32 v107, v36
	v_mov_b32_e32 v116, v36
	v_mov_b32_e32 v117, v36
	v_mov_b32_e32 v118, v36
	v_mov_b32_e32 v119, v36
	v_mov_b32_e32 v120, v36
	v_mov_b32_e32 v121, v36
	v_mov_b32_e32 v122, v36
	v_mov_b32_e32 v123, v36
	v_mov_b32_e32 v132, v36
	v_mov_b32_e32 v133, v36
	v_mov_b32_e32 v134, v36
	v_mov_b32_e32 v135, v36
	v_mov_b32_e32 v136, v36
	v_mov_b32_e32 v137, v36
	v_mov_b32_e32 v138, v36
	v_mov_b32_e32 v139, v36
	v_mov_b32_e32 v148, v36
	v_mov_b32_e32 v149, v36
	v_mov_b32_e32 v150, v36
	v_mov_b32_e32 v151, v36
	v_mov_b32_e32 v152, v36
	v_mov_b32_e32 v153, v36
	v_mov_b32_e32 v154, v36
	v_mov_b32_e32 v155, v36
	v_mov_b32_e32 v108, v36
	v_mov_b32_e32 v109, v36
	v_mov_b32_e32 v110, v36
	v_mov_b32_e32 v111, v36
	v_mov_b32_e32 v112, v36
	v_mov_b32_e32 v113, v36
	v_mov_b32_e32 v114, v36
	v_mov_b32_e32 v115, v36
	v_mov_b32_e32 v124, v36
	v_mov_b32_e32 v125, v36
	v_mov_b32_e32 v126, v36
	v_mov_b32_e32 v127, v36
	v_mov_b32_e32 v128, v36
	v_mov_b32_e32 v129, v36
	v_mov_b32_e32 v130, v36
	v_mov_b32_e32 v131, v36
	v_mov_b32_e32 v140, v36
	v_mov_b32_e32 v141, v36
	v_mov_b32_e32 v142, v36
	v_mov_b32_e32 v143, v36
	v_mov_b32_e32 v144, v36
	v_mov_b32_e32 v145, v36
	v_mov_b32_e32 v146, v36
	v_mov_b32_e32 v147, v36
	v_mov_b32_e32 v156, v36
	v_mov_b32_e32 v157, v36
	v_mov_b32_e32 v158, v36
	v_mov_b32_e32 v159, v36
	v_mov_b32_e32 v160, v36
	v_mov_b32_e32 v161, v36
	v_mov_b32_e32 v162, v36
	v_mov_b32_e32 v163, v36
	v_add_u32_e32 v2, 0x10000, v202
.LBB0_707:
	s_add_u32 s34, s50, 0xfff80080
	s_addc_u32 s35, s51, -1
	s_add_i32 s61, 0, 0x10000
	s_cmp_eq_u32 s60, 4
	s_cselect_b32 s55, s23, s35
	s_cselect_b32 s54, s22, s34
	s_cselect_b32 s53, s43, s59
	s_cselect_b32 s52, s42, s21
	s_add_i32 s62, 0, 0x14000
	ds_read_b128 v[164:167], v2 offset:0
	ds_read_b128 v[168:171], v2 offset:1024
	ds_read_b128 v[172:175], v2 offset:2048
	ds_read_b128 v[176:179], v2 offset:3072
	ds_read_b128 v[192:195], v2 offset:16384
	ds_read_b128 v[196:199], v2 offset:17408
	ds_read_b128 v[204:207], v2 offset:18432
	ds_read_b128 v[210:213], v2 offset:19456
	s_add_i32 m0, s29, 0xc000
	ds_read_b128 v[216:219], v203
	ds_read_b128 v[220:223], v203 offset:1024
	ds_read_b128 v[224:227], v203 offset:2048
	ds_read_b128 v[228:231], v203 offset:3072
	ds_read_b128 v[232:235], v203 offset:4096
	ds_read_b128 v[236:239], v203 offset:5120
	ds_read_b128 v[240:243], v203 offset:6144
	ds_read_b128 v[244:247], v203 offset:7168
	global_load_lds_dwordx4 v188, s[50:51]
	s_add_i32 m0, s29, 0xe000
	s_nop 0
	global_load_lds_dwordx4 v190, s[50:51]
	s_waitcnt vmcnt(8) lgkmcnt(0)
	s_barrier
	v_mfma_f32_16x16x32_bf16 v[160:163], v[164:167], v[216:219], v[160:163]
	v_mfma_f32_16x16x32_bf16 v[156:159], v[172:175], v[216:219], v[156:159]
	v_mfma_f32_16x16x32_bf16 v[144:147], v[164:167], v[224:227], v[144:147]
	v_mfma_f32_16x16x32_bf16 v[140:143], v[172:175], v[224:227], v[140:143]
	v_mfma_f32_16x16x32_bf16 v[128:131], v[164:167], v[232:235], v[128:131]
	v_mfma_f32_16x16x32_bf16 v[124:127], v[172:175], v[232:235], v[124:127]
	v_mfma_f32_16x16x32_bf16 v[112:115], v[164:167], v[240:243], v[112:115]
	v_mfma_f32_16x16x32_bf16 v[108:111], v[172:175], v[240:243], v[108:111]
	v_mfma_f32_16x16x32_bf16 v[160:163], v[168:171], v[220:223], v[160:163]
	v_mfma_f32_16x16x32_bf16 v[156:159], v[176:179], v[220:223], v[156:159]
	v_mfma_f32_16x16x32_bf16 v[144:147], v[168:171], v[228:231], v[144:147]
	v_mfma_f32_16x16x32_bf16 v[140:143], v[176:179], v[228:231], v[140:143]
	v_mfma_f32_16x16x32_bf16 v[128:131], v[168:171], v[236:239], v[128:131]
	v_mfma_f32_16x16x32_bf16 v[124:127], v[176:179], v[236:239], v[124:127]
	v_mfma_f32_16x16x32_bf16 v[112:115], v[168:171], v[244:247], v[112:115]
	v_mfma_f32_16x16x32_bf16 v[108:111], v[176:179], v[244:247], v[108:111]
	v_mfma_f32_16x16x32_bf16 v[152:155], v[192:195], v[216:219], v[152:155]
	v_mfma_f32_16x16x32_bf16 v[148:151], v[204:207], v[216:219], v[148:151]
	v_mfma_f32_16x16x32_bf16 v[136:139], v[192:195], v[224:227], v[136:139]
	v_mfma_f32_16x16x32_bf16 v[132:135], v[204:207], v[224:227], v[132:135]
	v_mfma_f32_16x16x32_bf16 v[120:123], v[192:195], v[232:235], v[120:123]
	v_mfma_f32_16x16x32_bf16 v[116:119], v[204:207], v[232:235], v[116:119]
	v_mfma_f32_16x16x32_bf16 v[104:107], v[192:195], v[240:243], v[104:107]
	v_mfma_f32_16x16x32_bf16 v[100:103], v[204:207], v[240:243], v[100:103]
	v_mfma_f32_16x16x32_bf16 v[152:155], v[196:199], v[220:223], v[152:155]
	v_mfma_f32_16x16x32_bf16 v[148:151], v[210:213], v[220:223], v[148:151]
	v_mfma_f32_16x16x32_bf16 v[136:139], v[196:199], v[228:231], v[136:139]
	v_mfma_f32_16x16x32_bf16 v[132:135], v[210:213], v[228:231], v[132:135]
	v_mfma_f32_16x16x32_bf16 v[120:123], v[196:199], v[236:239], v[120:123]
	v_mfma_f32_16x16x32_bf16 v[116:119], v[210:213], v[236:239], v[116:119]
	v_mfma_f32_16x16x32_bf16 v[104:107], v[196:199], v[244:247], v[104:107]
	v_mfma_f32_16x16x32_bf16 v[100:103], v[210:213], v[244:247], v[100:103]
	s_barrier
	s_add_i32 s34, s61, s0
	s_mov_b32 m0, s34
	ds_read_b128 v[216:219], v203 offset:16384
	ds_read_b128 v[220:223], v203 offset:17408
	ds_read_b128 v[224:227], v203 offset:18432
	ds_read_b128 v[228:231], v203 offset:19456
	ds_read_b128 v[232:235], v203 offset:20480
	ds_read_b128 v[236:239], v203 offset:21504
	ds_read_b128 v[240:243], v203 offset:22528
	ds_read_b128 v[244:247], v203 offset:23552
	global_load_lds_dwordx4 v180, s[52:53]
	s_add_i32 m0, s34, 0x2000
	s_add_u32 s34, s52, 0x4000
	s_addc_u32 s35, s53, 0
	s_add_i32 s61, s62, s0
	global_load_lds_dwordx4 v184, s[52:53]
	s_mov_b32 m0, s61
	v_lshl_add_u64 v[248:249], s[54:55], 0, v[186:187]
	global_load_lds_dwordx4 v180, s[34:35]
	s_add_i32 m0, s61, 0x2000
	s_nop 0
	global_load_lds_dwordx4 v184, s[34:35]
	v_lshl_add_u64 v[200:201], s[54:55], 0, v[182:183]
	s_mov_b32 m0, s29
	s_nop 0
	global_load_lds_dwordx4 v182, s[54:55]
	s_mov_b32 m0, s45
	s_nop 0
	global_load_lds_dwordx4 v186, s[54:55]
	s_waitcnt vmcnt(8) lgkmcnt(0)
	s_barrier
	v_mfma_f32_16x16x32_bf16 v[96:99], v[164:167], v[216:219], v[96:99]
	v_mfma_f32_16x16x32_bf16 v[92:95], v[172:175], v[216:219], v[92:95]
	v_mfma_f32_16x16x32_bf16 v[84:87], v[164:167], v[224:227], v[84:87]
	v_mfma_f32_16x16x32_bf16 v[76:79], v[172:175], v[224:227], v[76:79]
	v_mfma_f32_16x16x32_bf16 v[68:71], v[164:167], v[232:235], v[68:71]
	v_mfma_f32_16x16x32_bf16 v[60:63], v[172:175], v[232:235], v[60:63]
	v_mfma_f32_16x16x32_bf16 v[52:55], v[164:167], v[240:243], v[52:55]
	v_mfma_f32_16x16x32_bf16 v[44:47], v[172:175], v[240:243], v[44:47]
	v_mfma_f32_16x16x32_bf16 v[96:99], v[168:171], v[220:223], v[96:99]
	v_mfma_f32_16x16x32_bf16 v[92:95], v[176:179], v[220:223], v[92:95]
	v_mfma_f32_16x16x32_bf16 v[84:87], v[168:171], v[228:231], v[84:87]
	v_mfma_f32_16x16x32_bf16 v[76:79], v[176:179], v[228:231], v[76:79]
	v_mfma_f32_16x16x32_bf16 v[68:71], v[168:171], v[236:239], v[68:71]
	v_mfma_f32_16x16x32_bf16 v[60:63], v[176:179], v[236:239], v[60:63]
	v_mfma_f32_16x16x32_bf16 v[52:55], v[168:171], v[244:247], v[52:55]
	v_mfma_f32_16x16x32_bf16 v[44:47], v[176:179], v[244:247], v[44:47]
	v_mfma_f32_16x16x32_bf16 v[88:91], v[192:195], v[216:219], v[88:91]
	v_mfma_f32_16x16x32_bf16 v[80:83], v[204:207], v[216:219], v[80:83]
	v_mfma_f32_16x16x32_bf16 v[72:75], v[192:195], v[224:227], v[72:75]
	v_mfma_f32_16x16x32_bf16 v[64:67], v[204:207], v[224:227], v[64:67]
	v_mfma_f32_16x16x32_bf16 v[56:59], v[192:195], v[232:235], v[56:59]
	v_mfma_f32_16x16x32_bf16 v[48:51], v[204:207], v[232:235], v[48:51]
	v_mfma_f32_16x16x32_bf16 v[40:43], v[192:195], v[240:243], v[40:43]
	v_mfma_f32_16x16x32_bf16 v[36:39], v[204:207], v[240:243], v[36:39]
	v_mfma_f32_16x16x32_bf16 v[88:91], v[196:199], v[220:223], v[88:91]
	v_mfma_f32_16x16x32_bf16 v[80:83], v[210:213], v[220:223], v[80:83]
	v_mfma_f32_16x16x32_bf16 v[72:75], v[196:199], v[228:231], v[72:75]
	v_mfma_f32_16x16x32_bf16 v[64:67], v[210:213], v[228:231], v[64:67]
	v_mfma_f32_16x16x32_bf16 v[56:59], v[196:199], v[236:239], v[56:59]
	v_mfma_f32_16x16x32_bf16 v[48:51], v[210:213], v[236:239], v[48:51]
	v_mfma_f32_16x16x32_bf16 v[40:43], v[196:199], v[244:247], v[40:43]
	v_mfma_f32_16x16x32_bf16 v[36:39], v[210:213], v[244:247], v[36:39]
	s_barrier
	s_add_i32 s61, 0, 0x18000
	s_add_i32 s62, 0, 0x1c000
	ds_read_b128 v[164:167], v2 offset:32768
	ds_read_b128 v[168:171], v2 offset:33792
	ds_read_b128 v[172:175], v2 offset:34816
	ds_read_b128 v[176:179], v2 offset:35840
	ds_read_b128 v[192:195], v2 offset:49152
	ds_read_b128 v[196:199], v2 offset:50176
	ds_read_b128 v[204:207], v2 offset:51200
	ds_read_b128 v[210:213], v2 offset:52224
	s_add_u32 s34, s54, 0x80000
	s_addc_u32 s35, s55, 0
	s_mov_b32 m0, s82
	ds_read_b128 v[216:219], v203 offset:32768
	ds_read_b128 v[220:223], v203 offset:33792
	ds_read_b128 v[224:227], v203 offset:34816
	ds_read_b128 v[228:231], v203 offset:35840
	ds_read_b128 v[232:235], v203 offset:36864
	ds_read_b128 v[236:239], v203 offset:37888
	ds_read_b128 v[240:243], v203 offset:38912
	ds_read_b128 v[244:247], v203 offset:39936
	global_load_lds_dwordx4 v182, s[34:35]
	s_mov_b32 m0, s90
	s_nop 0
	global_load_lds_dwordx4 v186, s[34:35]
	s_waitcnt vmcnt(8) lgkmcnt(0)
	s_barrier
	v_mfma_f32_16x16x32_bf16 v[160:163], v[164:167], v[216:219], v[160:163]
	v_mfma_f32_16x16x32_bf16 v[156:159], v[172:175], v[216:219], v[156:159]
	v_mfma_f32_16x16x32_bf16 v[144:147], v[164:167], v[224:227], v[144:147]
	v_mfma_f32_16x16x32_bf16 v[140:143], v[172:175], v[224:227], v[140:143]
	v_mfma_f32_16x16x32_bf16 v[128:131], v[164:167], v[232:235], v[128:131]
	v_mfma_f32_16x16x32_bf16 v[124:127], v[172:175], v[232:235], v[124:127]
	v_mfma_f32_16x16x32_bf16 v[112:115], v[164:167], v[240:243], v[112:115]
	v_mfma_f32_16x16x32_bf16 v[108:111], v[172:175], v[240:243], v[108:111]
	v_mfma_f32_16x16x32_bf16 v[160:163], v[168:171], v[220:223], v[160:163]
	v_mfma_f32_16x16x32_bf16 v[156:159], v[176:179], v[220:223], v[156:159]
	v_mfma_f32_16x16x32_bf16 v[144:147], v[168:171], v[228:231], v[144:147]
	v_mfma_f32_16x16x32_bf16 v[140:143], v[176:179], v[228:231], v[140:143]
	v_mfma_f32_16x16x32_bf16 v[128:131], v[168:171], v[236:239], v[128:131]
	v_mfma_f32_16x16x32_bf16 v[124:127], v[176:179], v[236:239], v[124:127]
	v_mfma_f32_16x16x32_bf16 v[112:115], v[168:171], v[244:247], v[112:115]
	v_mfma_f32_16x16x32_bf16 v[108:111], v[176:179], v[244:247], v[108:111]
	v_mfma_f32_16x16x32_bf16 v[152:155], v[192:195], v[216:219], v[152:155]
	v_mfma_f32_16x16x32_bf16 v[148:151], v[204:207], v[216:219], v[148:151]
	v_mfma_f32_16x16x32_bf16 v[136:139], v[192:195], v[224:227], v[136:139]
	v_mfma_f32_16x16x32_bf16 v[132:135], v[204:207], v[224:227], v[132:135]
	v_mfma_f32_16x16x32_bf16 v[120:123], v[192:195], v[232:235], v[120:123]
	v_mfma_f32_16x16x32_bf16 v[116:119], v[204:207], v[232:235], v[116:119]
	v_mfma_f32_16x16x32_bf16 v[104:107], v[192:195], v[240:243], v[104:107]
	v_mfma_f32_16x16x32_bf16 v[100:103], v[204:207], v[240:243], v[100:103]
	v_mfma_f32_16x16x32_bf16 v[152:155], v[196:199], v[220:223], v[152:155]
	v_mfma_f32_16x16x32_bf16 v[148:151], v[210:213], v[220:223], v[148:151]
	v_mfma_f32_16x16x32_bf16 v[136:139], v[196:199], v[228:231], v[136:139]
	v_mfma_f32_16x16x32_bf16 v[132:135], v[210:213], v[228:231], v[132:135]
	v_mfma_f32_16x16x32_bf16 v[120:123], v[196:199], v[236:239], v[120:123]
	v_mfma_f32_16x16x32_bf16 v[116:119], v[210:213], v[236:239], v[116:119]
	v_mfma_f32_16x16x32_bf16 v[104:107], v[196:199], v[244:247], v[104:107]
	v_mfma_f32_16x16x32_bf16 v[100:103], v[210:213], v[244:247], v[100:103]
	s_barrier
	s_add_u32 s34, s52, 0x8000
	s_addc_u32 s35, s53, 0
	s_add_i32 s54, s61, s0
	s_mov_b32 m0, s54
	ds_read_b128 v[216:219], v203 offset:49152
	ds_read_b128 v[220:223], v203 offset:50176
	ds_read_b128 v[224:227], v203 offset:51200
	ds_read_b128 v[228:231], v203 offset:52224
	ds_read_b128 v[232:235], v203 offset:53248
	ds_read_b128 v[236:239], v203 offset:54272
	ds_read_b128 v[240:243], v203 offset:55296
	ds_read_b128 v[244:247], v203 offset:56320
	global_load_lds_dwordx4 v180, s[34:35]
	s_add_i32 m0, s54, 0x2000
	v_lshl_add_u64 v[250:251], s[34:35], 0, v[184:185]
	s_add_u32 s34, s52, 0xc000
	s_addc_u32 s35, s53, 0
	s_add_i32 s52, s62, s0
	global_load_lds_dwordx4 v[250:251], off
	s_mov_b32 m0, s52
	v_lshl_add_u64 v[200:201], v[200:201], 0, s[92:93]
	global_load_lds_dwordx4 v180, s[34:35]
	s_add_i32 m0, s52, 0x2000
	s_nop 0
	global_load_lds_dwordx4 v184, s[34:35]
	s_mov_b32 m0, s91
	s_nop 0
	global_load_lds_dwordx4 v[200:201], off
	v_lshl_add_u64 v[200:201], v[248:249], 0, s[92:93]
	s_mov_b32 m0, s30
	s_nop 0
	global_load_lds_dwordx4 v[200:201], off
	s_waitcnt vmcnt(8) lgkmcnt(0)
	s_barrier
	v_mfma_f32_16x16x32_bf16 v[96:99], v[164:167], v[216:219], v[96:99]
	v_mfma_f32_16x16x32_bf16 v[92:95], v[172:175], v[216:219], v[92:95]
	v_mfma_f32_16x16x32_bf16 v[84:87], v[164:167], v[224:227], v[84:87]
	v_mfma_f32_16x16x32_bf16 v[76:79], v[172:175], v[224:227], v[76:79]
	v_mfma_f32_16x16x32_bf16 v[68:71], v[164:167], v[232:235], v[68:71]
	v_mfma_f32_16x16x32_bf16 v[60:63], v[172:175], v[232:235], v[60:63]
	v_mfma_f32_16x16x32_bf16 v[52:55], v[164:167], v[240:243], v[52:55]
	v_mfma_f32_16x16x32_bf16 v[44:47], v[172:175], v[240:243], v[44:47]
	v_mfma_f32_16x16x32_bf16 v[96:99], v[168:171], v[220:223], v[96:99]
	v_mfma_f32_16x16x32_bf16 v[92:95], v[176:179], v[220:223], v[92:95]
	v_mfma_f32_16x16x32_bf16 v[84:87], v[168:171], v[228:231], v[84:87]
	v_mfma_f32_16x16x32_bf16 v[76:79], v[176:179], v[228:231], v[76:79]
	v_mfma_f32_16x16x32_bf16 v[68:71], v[168:171], v[236:239], v[68:71]
	v_mfma_f32_16x16x32_bf16 v[60:63], v[176:179], v[236:239], v[60:63]
	v_mfma_f32_16x16x32_bf16 v[52:55], v[168:171], v[244:247], v[52:55]
	v_mfma_f32_16x16x32_bf16 v[44:47], v[176:179], v[244:247], v[44:47]
	v_mfma_f32_16x16x32_bf16 v[88:91], v[192:195], v[216:219], v[88:91]
	v_mfma_f32_16x16x32_bf16 v[80:83], v[204:207], v[216:219], v[80:83]
	v_mfma_f32_16x16x32_bf16 v[72:75], v[192:195], v[224:227], v[72:75]
	v_mfma_f32_16x16x32_bf16 v[64:67], v[204:207], v[224:227], v[64:67]
	v_mfma_f32_16x16x32_bf16 v[56:59], v[192:195], v[232:235], v[56:59]
	v_mfma_f32_16x16x32_bf16 v[48:51], v[204:207], v[232:235], v[48:51]
	v_mfma_f32_16x16x32_bf16 v[40:43], v[192:195], v[240:243], v[40:43]
	v_mfma_f32_16x16x32_bf16 v[36:39], v[204:207], v[240:243], v[36:39]
	v_mfma_f32_16x16x32_bf16 v[88:91], v[196:199], v[220:223], v[88:91]
	v_mfma_f32_16x16x32_bf16 v[80:83], v[210:213], v[220:223], v[80:83]
	v_mfma_f32_16x16x32_bf16 v[72:75], v[196:199], v[228:231], v[72:75]
	v_mfma_f32_16x16x32_bf16 v[64:67], v[210:213], v[228:231], v[64:67]
	v_mfma_f32_16x16x32_bf16 v[56:59], v[196:199], v[236:239], v[56:59]
	v_mfma_f32_16x16x32_bf16 v[48:51], v[210:213], v[236:239], v[48:51]
	v_mfma_f32_16x16x32_bf16 v[40:43], v[196:199], v[244:247], v[40:43]
	v_mfma_f32_16x16x32_bf16 v[36:39], v[210:213], v[244:247], v[36:39]
	s_barrier
	s_add_i32 s60, s60, 2
	s_add_u32 s21, s21, 0x10000
	s_addc_u32 s59, s59, 0
	s_add_u32 s50, s50, 0x100
	s_addc_u32 s51, s51, 0
	s_cmp_gt_u32 s60, 5
	s_cbranch_scc0 .LBB0_707
	s_and_b64 vcc, exec, s[46:47]
	s_cbranch_vccz .LBB0_710
	s_barrier

.LBB0_787:
	s_add_u32 s15, s52, 0x10000
	s_addc_u32 s51, s53, 0
	s_add_u32 s48, s48, 0x80080
	s_addc_u32 s49, s49, 0
	s_mov_b32 s56, -2
	v_add_u32_e32 v200, 0x10000, v198
.LBB0_788:
	s_add_u32 s34, s48, 0xfff80080
	s_addc_u32 s35, s49, -1
	s_add_i32 s57, 0, 0x10000
	s_cmp_eq_u32 s56, 28
	s_cselect_b32 s55, s23, s35
	s_cselect_b32 s54, s22, s34
	s_cselect_b32 s53, s43, s51
	s_cselect_b32 s52, s42, s15
	s_add_i32 s69, 0, 0x14000
	ds_read_b128 v[136:139], v200 offset:0
	ds_read_b128 v[140:143], v200 offset:1024
	ds_read_b128 v[144:147], v200 offset:2048
	ds_read_b128 v[148:151], v200 offset:3072
	ds_read_b128 v[152:155], v200 offset:16384
	ds_read_b128 v[156:159], v200 offset:17408
	ds_read_b128 v[160:163], v200 offset:18432
	ds_read_b128 v[174:177], v200 offset:19456
	s_add_i32 m0, s29, 0xc000
	ds_read_b128 v[178:181], v199
	ds_read_b128 v[182:185], v199 offset:1024
	ds_read_b128 v[186:189], v199 offset:2048
	ds_read_b128 v[190:193], v199 offset:3072
	ds_read_b128 v[194:197], v199 offset:4096
	ds_read_b128 v[210:213], v199 offset:5120
	ds_read_b128 v[240:243], v199 offset:6144
	ds_read_b128 v[244:247], v199 offset:7168
	global_load_lds_dwordx4 v170, s[48:49]
	s_add_i32 m0, s29, 0xe000
	s_nop 0
	global_load_lds_dwordx4 v172, s[48:49]
	s_waitcnt vmcnt(8) lgkmcnt(0)
	s_barrier
	v_mfma_f32_16x16x32_bf16 v[132:135], v[136:139], v[178:181], v[132:135]
	v_mfma_f32_16x16x32_bf16 v[128:131], v[144:147], v[178:181], v[128:131]
	v_mfma_f32_16x16x32_bf16 v[124:127], v[136:139], v[186:189], v[124:127]
	v_mfma_f32_16x16x32_bf16 v[120:123], v[144:147], v[186:189], v[120:123]
	v_mfma_f32_16x16x32_bf16 v[116:119], v[136:139], v[194:197], v[116:119]
	v_mfma_f32_16x16x32_bf16 v[112:115], v[144:147], v[194:197], v[112:115]
	v_mfma_f32_16x16x32_bf16 v[108:111], v[136:139], v[240:243], v[108:111]
	v_mfma_f32_16x16x32_bf16 v[104:107], v[144:147], v[240:243], v[104:107]
	v_mfma_f32_16x16x32_bf16 v[132:135], v[140:143], v[182:185], v[132:135]
	v_mfma_f32_16x16x32_bf16 v[128:131], v[148:151], v[182:185], v[128:131]
	v_mfma_f32_16x16x32_bf16 v[124:127], v[140:143], v[190:193], v[124:127]
	v_mfma_f32_16x16x32_bf16 v[120:123], v[148:151], v[190:193], v[120:123]
	v_mfma_f32_16x16x32_bf16 v[116:119], v[140:143], v[210:213], v[116:119]
	v_mfma_f32_16x16x32_bf16 v[112:115], v[148:151], v[210:213], v[112:115]
	v_mfma_f32_16x16x32_bf16 v[108:111], v[140:143], v[244:247], v[108:111]
	v_mfma_f32_16x16x32_bf16 v[104:107], v[148:151], v[244:247], v[104:107]
	v_mfma_f32_16x16x32_bf16 v[100:103], v[152:155], v[178:181], v[100:103]
	v_mfma_f32_16x16x32_bf16 v[96:99], v[160:163], v[178:181], v[96:99]
	v_mfma_f32_16x16x32_bf16 v[92:95], v[152:155], v[186:189], v[92:95]
	v_mfma_f32_16x16x32_bf16 v[88:91], v[160:163], v[186:189], v[88:91]
	v_mfma_f32_16x16x32_bf16 v[84:87], v[152:155], v[194:197], v[84:87]
	v_mfma_f32_16x16x32_bf16 v[80:83], v[160:163], v[194:197], v[80:83]
	v_mfma_f32_16x16x32_bf16 v[72:75], v[152:155], v[240:243], v[72:75]
	v_mfma_f32_16x16x32_bf16 v[64:67], v[160:163], v[240:243], v[64:67]
	v_mfma_f32_16x16x32_bf16 v[100:103], v[156:159], v[182:185], v[100:103]
	v_mfma_f32_16x16x32_bf16 v[96:99], v[174:177], v[182:185], v[96:99]
	v_mfma_f32_16x16x32_bf16 v[92:95], v[156:159], v[190:193], v[92:95]
	v_mfma_f32_16x16x32_bf16 v[88:91], v[174:177], v[190:193], v[88:91]
	v_mfma_f32_16x16x32_bf16 v[84:87], v[156:159], v[210:213], v[84:87]
	v_mfma_f32_16x16x32_bf16 v[80:83], v[174:177], v[210:213], v[80:83]
	v_mfma_f32_16x16x32_bf16 v[72:75], v[156:159], v[244:247], v[72:75]
	v_mfma_f32_16x16x32_bf16 v[64:67], v[174:177], v[244:247], v[64:67]
	s_barrier
	s_add_i32 s34, s57, s0
	s_mov_b32 m0, s34
	ds_read_b128 v[178:181], v199 offset:16384
	ds_read_b128 v[182:185], v199 offset:17408
	ds_read_b128 v[186:189], v199 offset:18432
	ds_read_b128 v[190:193], v199 offset:19456
	ds_read_b128 v[194:197], v199 offset:20480
	ds_read_b128 v[210:213], v199 offset:21504
	ds_read_b128 v[240:243], v199 offset:22528
	ds_read_b128 v[244:247], v199 offset:23552
	global_load_lds_dwordx4 v32, s[52:53]
	s_add_i32 m0, s34, 0x2000
	s_add_u32 s34, s52, 0x4000
	s_addc_u32 s35, s53, 0
	s_add_i32 s57, s69, s0
	global_load_lds_dwordx4 v166, s[52:53]
	s_mov_b32 m0, s57
	v_lshl_add_u64 v[248:249], s[54:55], 0, v[164:165]
	global_load_lds_dwordx4 v32, s[34:35]
	s_add_i32 m0, s57, 0x2000
	v_lshl_add_u64 v[250:251], s[54:55], 0, v[168:169]
	global_load_lds_dwordx4 v166, s[34:35]
	s_mov_b32 m0, s29
	s_nop 0
	global_load_lds_dwordx4 v164, s[54:55]
	s_mov_b32 m0, s45
	s_nop 0
	global_load_lds_dwordx4 v168, s[54:55]
	s_waitcnt vmcnt(8) lgkmcnt(0)
	s_barrier
	v_mfma_f32_16x16x32_bf16 v[76:79], v[136:139], v[178:181], v[76:79]
	v_mfma_f32_16x16x32_bf16 v[68:71], v[144:147], v[178:181], v[68:71]
	v_mfma_f32_16x16x32_bf16 v[60:63], v[136:139], v[186:189], v[60:63]
	v_mfma_f32_16x16x32_bf16 v[56:59], v[144:147], v[186:189], v[56:59]
	v_mfma_f32_16x16x32_bf16 v[52:55], v[136:139], v[194:197], v[52:55]
	v_mfma_f32_16x16x32_bf16 v[48:51], v[144:147], v[194:197], v[48:51]
	v_mfma_f32_16x16x32_bf16 v[44:47], v[136:139], v[240:243], v[44:47]
	v_mfma_f32_16x16x32_bf16 v[40:43], v[144:147], v[240:243], v[40:43]
	v_mfma_f32_16x16x32_bf16 v[76:79], v[140:143], v[182:185], v[76:79]
	v_mfma_f32_16x16x32_bf16 v[68:71], v[148:151], v[182:185], v[68:71]
	v_mfma_f32_16x16x32_bf16 v[60:63], v[140:143], v[190:193], v[60:63]
	v_mfma_f32_16x16x32_bf16 v[56:59], v[148:151], v[190:193], v[56:59]
	v_mfma_f32_16x16x32_bf16 v[52:55], v[140:143], v[210:213], v[52:55]
	v_mfma_f32_16x16x32_bf16 v[48:51], v[148:151], v[210:213], v[48:51]
	v_mfma_f32_16x16x32_bf16 v[44:47], v[140:143], v[244:247], v[44:47]
	v_mfma_f32_16x16x32_bf16 v[40:43], v[148:151], v[244:247], v[40:43]
	v_mfma_f32_16x16x32_bf16 v[36:39], v[152:155], v[178:181], v[36:39]
	v_mfma_f32_16x16x32_bf16 v[28:31], v[160:163], v[178:181], v[28:31]
	v_mfma_f32_16x16x32_bf16 v[24:27], v[152:155], v[186:189], v[24:27]
	v_mfma_f32_16x16x32_bf16 v[20:23], v[160:163], v[186:189], v[20:23]
	v_mfma_f32_16x16x32_bf16 v[16:19], v[152:155], v[194:197], v[16:19]
	v_mfma_f32_16x16x32_bf16 v[12:15], v[160:163], v[194:197], v[12:15]
	v_mfma_f32_16x16x32_bf16 v[8:11], v[152:155], v[240:243], v[8:11]
	v_mfma_f32_16x16x32_bf16 v[2:5], v[160:163], v[240:243], v[4:7]
	v_mfma_f32_16x16x32_bf16 v[36:39], v[156:159], v[182:185], v[36:39]
	v_mfma_f32_16x16x32_bf16 v[28:31], v[174:177], v[182:185], v[28:31]
	v_mfma_f32_16x16x32_bf16 v[24:27], v[156:159], v[190:193], v[24:27]
	v_mfma_f32_16x16x32_bf16 v[20:23], v[174:177], v[190:193], v[20:23]
	v_mfma_f32_16x16x32_bf16 v[16:19], v[156:159], v[210:213], v[16:19]
	v_mfma_f32_16x16x32_bf16 v[12:15], v[174:177], v[210:213], v[12:15]
	v_mfma_f32_16x16x32_bf16 v[8:11], v[156:159], v[244:247], v[8:11]
	v_mfma_f32_16x16x32_bf16 v[2:5], v[174:177], v[244:247], v[2:5]
	s_barrier
	s_add_i32 s57, 0, 0x18000
	s_add_i32 s69, 0, 0x1c000
	ds_read_b128 v[136:139], v200 offset:32768
	ds_read_b128 v[140:143], v200 offset:33792
	ds_read_b128 v[144:147], v200 offset:34816
	ds_read_b128 v[148:151], v200 offset:35840
	ds_read_b128 v[152:155], v200 offset:49152
	ds_read_b128 v[156:159], v200 offset:50176
	ds_read_b128 v[160:163], v200 offset:51200
	ds_read_b128 v[174:177], v200 offset:52224
	s_add_u32 s34, s54, 0x80000
	s_addc_u32 s35, s55, 0
	s_mov_b32 m0, s82
	ds_read_b128 v[178:181], v199 offset:32768
	ds_read_b128 v[182:185], v199 offset:33792
	ds_read_b128 v[186:189], v199 offset:34816
	ds_read_b128 v[190:193], v199 offset:35840
	ds_read_b128 v[194:197], v199 offset:36864
	ds_read_b128 v[210:213], v199 offset:37888
	ds_read_b128 v[240:243], v199 offset:38912
	ds_read_b128 v[244:247], v199 offset:39936
	global_load_lds_dwordx4 v164, s[34:35]
	s_mov_b32 m0, s90
	s_nop 0
	global_load_lds_dwordx4 v168, s[34:35]
	s_waitcnt vmcnt(8) lgkmcnt(0)
	s_barrier
	v_mfma_f32_16x16x32_bf16 v[132:135], v[136:139], v[178:181], v[132:135]
	v_mfma_f32_16x16x32_bf16 v[128:131], v[144:147], v[178:181], v[128:131]
	v_mfma_f32_16x16x32_bf16 v[124:127], v[136:139], v[186:189], v[124:127]
	v_mfma_f32_16x16x32_bf16 v[120:123], v[144:147], v[186:189], v[120:123]
	v_mfma_f32_16x16x32_bf16 v[116:119], v[136:139], v[194:197], v[116:119]
	v_mfma_f32_16x16x32_bf16 v[112:115], v[144:147], v[194:197], v[112:115]
	v_mfma_f32_16x16x32_bf16 v[108:111], v[136:139], v[240:243], v[108:111]
	v_mfma_f32_16x16x32_bf16 v[104:107], v[144:147], v[240:243], v[104:107]
	v_mfma_f32_16x16x32_bf16 v[132:135], v[140:143], v[182:185], v[132:135]
	v_mfma_f32_16x16x32_bf16 v[128:131], v[148:151], v[182:185], v[128:131]
	v_mfma_f32_16x16x32_bf16 v[124:127], v[140:143], v[190:193], v[124:127]
	v_mfma_f32_16x16x32_bf16 v[120:123], v[148:151], v[190:193], v[120:123]
	v_mfma_f32_16x16x32_bf16 v[116:119], v[140:143], v[210:213], v[116:119]
	v_mfma_f32_16x16x32_bf16 v[112:115], v[148:151], v[210:213], v[112:115]
	v_mfma_f32_16x16x32_bf16 v[108:111], v[140:143], v[244:247], v[108:111]
	v_mfma_f32_16x16x32_bf16 v[104:107], v[148:151], v[244:247], v[104:107]
	v_mfma_f32_16x16x32_bf16 v[100:103], v[152:155], v[178:181], v[100:103]
	v_mfma_f32_16x16x32_bf16 v[96:99], v[160:163], v[178:181], v[96:99]
	v_mfma_f32_16x16x32_bf16 v[92:95], v[152:155], v[186:189], v[92:95]
	v_mfma_f32_16x16x32_bf16 v[88:91], v[160:163], v[186:189], v[88:91]
	v_mfma_f32_16x16x32_bf16 v[84:87], v[152:155], v[194:197], v[84:87]
	v_mfma_f32_16x16x32_bf16 v[80:83], v[160:163], v[194:197], v[80:83]
	v_mfma_f32_16x16x32_bf16 v[72:75], v[152:155], v[240:243], v[72:75]
	v_mfma_f32_16x16x32_bf16 v[64:67], v[160:163], v[240:243], v[64:67]
	v_mfma_f32_16x16x32_bf16 v[100:103], v[156:159], v[182:185], v[100:103]
	v_mfma_f32_16x16x32_bf16 v[96:99], v[174:177], v[182:185], v[96:99]
	v_mfma_f32_16x16x32_bf16 v[92:95], v[156:159], v[190:193], v[92:95]
	v_mfma_f32_16x16x32_bf16 v[88:91], v[174:177], v[190:193], v[88:91]
	v_mfma_f32_16x16x32_bf16 v[84:87], v[156:159], v[210:213], v[84:87]
	v_mfma_f32_16x16x32_bf16 v[80:83], v[174:177], v[210:213], v[80:83]
	v_mfma_f32_16x16x32_bf16 v[72:75], v[156:159], v[244:247], v[72:75]
	v_mfma_f32_16x16x32_bf16 v[64:67], v[174:177], v[244:247], v[64:67]
	s_barrier
	s_add_u32 s34, s52, 0x8000
	s_addc_u32 s35, s53, 0
	s_add_i32 s54, s57, s0
	s_mov_b32 m0, s54
	ds_read_b128 v[178:181], v199 offset:49152
	ds_read_b128 v[182:185], v199 offset:50176
	ds_read_b128 v[186:189], v199 offset:51200
	ds_read_b128 v[190:193], v199 offset:52224
	ds_read_b128 v[194:197], v199 offset:53248
	ds_read_b128 v[210:213], v199 offset:54272
	ds_read_b128 v[240:243], v199 offset:55296
	ds_read_b128 v[244:247], v199 offset:56320
	global_load_lds_dwordx4 v32, s[34:35]
	s_add_i32 m0, s54, 0x2000
	v_lshl_add_u64 v[6:7], s[34:35], 0, v[166:167]
	s_add_u32 s34, s52, 0xc000
	s_addc_u32 s35, s53, 0
	s_add_i32 s52, s69, s0
	global_load_lds_dwordx4 v[6:7], off
	s_mov_b32 m0, s52
	s_nop 0
	global_load_lds_dwordx4 v32, s[34:35]
	s_add_i32 m0, s52, 0x2000
	s_nop 0
	global_load_lds_dwordx4 v166, s[34:35]
	v_lshl_add_u64 v[6:7], v[248:249], 0, s[92:93]
	s_mov_b32 m0, s91
	s_nop 0
	global_load_lds_dwordx4 v[6:7], off
	v_lshl_add_u64 v[6:7], v[250:251], 0, s[92:93]
	s_mov_b32 m0, s30
	s_nop 0
	global_load_lds_dwordx4 v[6:7], off
	s_waitcnt vmcnt(8) lgkmcnt(0)
	s_barrier
	v_mfma_f32_16x16x32_bf16 v[76:79], v[136:139], v[178:181], v[76:79]
	v_mfma_f32_16x16x32_bf16 v[68:71], v[144:147], v[178:181], v[68:71]
	v_mfma_f32_16x16x32_bf16 v[60:63], v[136:139], v[186:189], v[60:63]
	v_mfma_f32_16x16x32_bf16 v[56:59], v[144:147], v[186:189], v[56:59]
	v_mfma_f32_16x16x32_bf16 v[52:55], v[136:139], v[194:197], v[52:55]
	v_mfma_f32_16x16x32_bf16 v[48:51], v[144:147], v[194:197], v[48:51]
	v_mfma_f32_16x16x32_bf16 v[44:47], v[136:139], v[240:243], v[44:47]
	v_mfma_f32_16x16x32_bf16 v[40:43], v[144:147], v[240:243], v[40:43]
	v_mfma_f32_16x16x32_bf16 v[76:79], v[140:143], v[182:185], v[76:79]
	v_mfma_f32_16x16x32_bf16 v[68:71], v[148:151], v[182:185], v[68:71]
	v_mfma_f32_16x16x32_bf16 v[60:63], v[140:143], v[190:193], v[60:63]
	v_mfma_f32_16x16x32_bf16 v[56:59], v[148:151], v[190:193], v[56:59]
	v_mfma_f32_16x16x32_bf16 v[52:55], v[140:143], v[210:213], v[52:55]
	v_mfma_f32_16x16x32_bf16 v[48:51], v[148:151], v[210:213], v[48:51]
	v_mfma_f32_16x16x32_bf16 v[44:47], v[140:143], v[244:247], v[44:47]
	v_mfma_f32_16x16x32_bf16 v[40:43], v[148:151], v[244:247], v[40:43]
	v_mfma_f32_16x16x32_bf16 v[36:39], v[152:155], v[178:181], v[36:39]
	v_mfma_f32_16x16x32_bf16 v[28:31], v[160:163], v[178:181], v[28:31]
	v_mfma_f32_16x16x32_bf16 v[24:27], v[152:155], v[186:189], v[24:27]
	v_mfma_f32_16x16x32_bf16 v[20:23], v[160:163], v[186:189], v[20:23]
	v_mfma_f32_16x16x32_bf16 v[16:19], v[152:155], v[194:197], v[16:19]
	v_mfma_f32_16x16x32_bf16 v[12:15], v[160:163], v[194:197], v[12:15]
	v_mfma_f32_16x16x32_bf16 v[6:9], v[152:155], v[240:243], v[8:11]
	v_mfma_f32_16x16x32_bf16 v[2:5], v[160:163], v[240:243], v[2:5]
	v_mfma_f32_16x16x32_bf16 v[36:39], v[156:159], v[182:185], v[36:39]
	v_mfma_f32_16x16x32_bf16 v[28:31], v[174:177], v[182:185], v[28:31]
	v_mfma_f32_16x16x32_bf16 v[24:27], v[156:159], v[190:193], v[24:27]
	v_mfma_f32_16x16x32_bf16 v[20:23], v[174:177], v[190:193], v[20:23]
	v_mfma_f32_16x16x32_bf16 v[16:19], v[156:159], v[210:213], v[16:19]
	v_mfma_f32_16x16x32_bf16 v[12:15], v[174:177], v[210:213], v[12:15]
	v_mfma_f32_16x16x32_bf16 v[8:11], v[156:159], v[244:247], v[6:9]
	v_mfma_f32_16x16x32_bf16 v[4:7], v[174:177], v[244:247], v[2:5]
	s_barrier
	s_add_i32 s56, s56, 2
	s_add_u32 s15, s15, 0x10000
	s_addc_u32 s51, s51, 0
	s_add_u32 s48, s48, 0x100
	s_addc_u32 s49, s49, 0
	s_cmp_gt_u32 s56, 29
	s_cbranch_scc0 .LBB0_788
	s_and_b64 vcc, exec, s[46:47]
	s_cbranch_vccz .LBB0_791
	s_barrier

.LBB0_876:
	s_add_u32 s13, s62, 0x10000
	v_mov_b32_e32 v2, 0
	s_addc_u32 s28, s63, 0
	s_mov_b32 s49, -2
	v_mov_b32_e32 v3, v2
	v_mov_b32_e32 v4, v2
	v_mov_b32_e32 v5, v2
	v_mov_b32_e32 v6, v2
	v_mov_b32_e32 v7, v2
	v_mov_b32_e32 v8, v2
	v_mov_b32_e32 v9, v2
	v_mov_b32_e32 v18, v2
	v_mov_b32_e32 v19, v2
	v_mov_b32_e32 v20, v2
	v_mov_b32_e32 v21, v2
	v_mov_b32_e32 v22, v2
	v_mov_b32_e32 v23, v2
	v_mov_b32_e32 v24, v2
	v_mov_b32_e32 v25, v2
	v_mov_b32_e32 v36, v2
	v_mov_b32_e32 v37, v2
	v_mov_b32_e32 v38, v2
	v_mov_b32_e32 v39, v2
	v_mov_b32_e32 v40, v2
	v_mov_b32_e32 v41, v2
	v_mov_b32_e32 v42, v2
	v_mov_b32_e32 v43, v2
	v_mov_b32_e32 v52, v2
	v_mov_b32_e32 v53, v2
	v_mov_b32_e32 v54, v2
	v_mov_b32_e32 v55, v2
	v_mov_b32_e32 v56, v2
	v_mov_b32_e32 v57, v2
	v_mov_b32_e32 v58, v2
	v_mov_b32_e32 v59, v2
	v_mov_b32_e32 v10, v2
	v_mov_b32_e32 v11, v2
	v_mov_b32_e32 v12, v2
	v_mov_b32_e32 v13, v2
	v_mov_b32_e32 v14, v2
	v_mov_b32_e32 v15, v2
	v_mov_b32_e32 v16, v2
	v_mov_b32_e32 v17, v2
	v_mov_b32_e32 v26, v2
	v_mov_b32_e32 v27, v2
	v_mov_b32_e32 v28, v2
	v_mov_b32_e32 v29, v2
	v_mov_b32_e32 v30, v2
	v_mov_b32_e32 v31, v2
	v_mov_b32_e32 v32, v2
	v_mov_b32_e32 v33, v2
	v_mov_b32_e32 v44, v2
	v_mov_b32_e32 v45, v2
	v_mov_b32_e32 v46, v2
	v_mov_b32_e32 v47, v2
	v_mov_b32_e32 v48, v2
	v_mov_b32_e32 v49, v2
	v_mov_b32_e32 v50, v2
	v_mov_b32_e32 v51, v2
	v_mov_b32_e32 v60, v2
	v_mov_b32_e32 v61, v2
	v_mov_b32_e32 v62, v2
	v_mov_b32_e32 v63, v2
	v_mov_b32_e32 v64, v2
	v_mov_b32_e32 v65, v2
	v_mov_b32_e32 v66, v2
	v_mov_b32_e32 v67, v2
	v_mov_b32_e32 v68, v2
	v_mov_b32_e32 v69, v2
	v_mov_b32_e32 v70, v2
	v_mov_b32_e32 v71, v2
	v_mov_b32_e32 v72, v2
	v_mov_b32_e32 v73, v2
	v_mov_b32_e32 v74, v2
	v_mov_b32_e32 v75, v2
	v_mov_b32_e32 v84, v2
	v_mov_b32_e32 v85, v2
	v_mov_b32_e32 v86, v2
	v_mov_b32_e32 v87, v2
	v_mov_b32_e32 v88, v2
	v_mov_b32_e32 v89, v2
	v_mov_b32_e32 v90, v2
	v_mov_b32_e32 v91, v2
	v_mov_b32_e32 v100, v2
	v_mov_b32_e32 v101, v2
	v_mov_b32_e32 v102, v2
	v_mov_b32_e32 v103, v2
	v_mov_b32_e32 v104, v2
	v_mov_b32_e32 v105, v2
	v_mov_b32_e32 v106, v2
	v_mov_b32_e32 v107, v2
	v_mov_b32_e32 v116, v2
	v_mov_b32_e32 v117, v2
	v_mov_b32_e32 v118, v2
	v_mov_b32_e32 v119, v2
	v_mov_b32_e32 v120, v2
	v_mov_b32_e32 v121, v2
	v_mov_b32_e32 v122, v2
	v_mov_b32_e32 v123, v2
	v_mov_b32_e32 v76, v2
	v_mov_b32_e32 v77, v2
	v_mov_b32_e32 v78, v2
	v_mov_b32_e32 v79, v2
	v_mov_b32_e32 v80, v2
	v_mov_b32_e32 v81, v2
	v_mov_b32_e32 v82, v2
	v_mov_b32_e32 v83, v2
	v_mov_b32_e32 v92, v2
	v_mov_b32_e32 v93, v2
	v_mov_b32_e32 v94, v2
	v_mov_b32_e32 v95, v2
	v_mov_b32_e32 v96, v2
	v_mov_b32_e32 v97, v2
	v_mov_b32_e32 v98, v2
	v_mov_b32_e32 v99, v2
	v_mov_b32_e32 v108, v2
	v_mov_b32_e32 v109, v2
	v_mov_b32_e32 v110, v2
	v_mov_b32_e32 v111, v2
	v_mov_b32_e32 v112, v2
	v_mov_b32_e32 v113, v2
	v_mov_b32_e32 v114, v2
	v_mov_b32_e32 v115, v2
	v_mov_b32_e32 v124, v2
	v_mov_b32_e32 v125, v2
	v_mov_b32_e32 v126, v2
	v_mov_b32_e32 v127, v2
	v_mov_b32_e32 v128, v2
	v_mov_b32_e32 v129, v2
	v_mov_b32_e32 v130, v2
	v_mov_b32_e32 v131, v2
	v_add_u32_e32 v190, 0x10000, v188
.LBB0_877:
	s_add_u32 s62, s60, 0x100
	s_addc_u32 s63, s61, 0
	s_add_i32 s34, 0, 0x10000
	s_cmp_eq_u32 s49, 60
	s_cselect_b32 s67, s51, s63
	s_cselect_b32 s66, s50, s62
	s_cselect_b32 s65, s53, s28
	s_cselect_b32 s64, s52, s13
	s_add_i32 s55, 0, 0x14000
	ds_read_b128 v[132:135], v190 offset:0
	ds_read_b128 v[136:139], v190 offset:1024
	ds_read_b128 v[140:143], v190 offset:2048
	ds_read_b128 v[144:147], v190 offset:3072
	ds_read_b128 v[148:151], v190 offset:16384
	ds_read_b128 v[152:155], v190 offset:17408
	ds_read_b128 v[168:171], v190 offset:18432
	ds_read_b128 v[172:175], v190 offset:19456
	s_add_i32 m0, s29, 0xc000
	ds_read_b128 v[176:179], v189
	ds_read_b128 v[180:183], v189 offset:1024
	ds_read_b128 v[184:187], v189 offset:2048
	ds_read_b128 v[192:195], v189 offset:3072
	ds_read_b128 v[210:213], v189 offset:4096
	ds_read_b128 v[234:237], v189 offset:5120
	ds_read_b128 v[238:241], v189 offset:6144
	ds_read_b128 v[242:245], v189 offset:7168
	global_load_lds_dwordx4 v164, s[60:61]
	s_add_i32 m0, s29, 0xe000
	s_nop 0
	global_load_lds_dwordx4 v166, s[60:61]
	s_waitcnt vmcnt(8) lgkmcnt(0)
	s_barrier
	v_mfma_f32_16x16x32_bf16 v[128:131], v[132:135], v[176:179], v[128:131]
	v_mfma_f32_16x16x32_bf16 v[124:127], v[140:143], v[176:179], v[124:127]
	v_mfma_f32_16x16x32_bf16 v[112:115], v[132:135], v[184:187], v[112:115]
	v_mfma_f32_16x16x32_bf16 v[108:111], v[140:143], v[184:187], v[108:111]
	v_mfma_f32_16x16x32_bf16 v[96:99], v[132:135], v[210:213], v[96:99]
	v_mfma_f32_16x16x32_bf16 v[92:95], v[140:143], v[210:213], v[92:95]
	v_mfma_f32_16x16x32_bf16 v[80:83], v[132:135], v[238:241], v[80:83]
	v_mfma_f32_16x16x32_bf16 v[76:79], v[140:143], v[238:241], v[76:79]
	v_mfma_f32_16x16x32_bf16 v[128:131], v[136:139], v[180:183], v[128:131]
	v_mfma_f32_16x16x32_bf16 v[124:127], v[144:147], v[180:183], v[124:127]
	v_mfma_f32_16x16x32_bf16 v[112:115], v[136:139], v[192:195], v[112:115]
	v_mfma_f32_16x16x32_bf16 v[108:111], v[144:147], v[192:195], v[108:111]
	v_mfma_f32_16x16x32_bf16 v[96:99], v[136:139], v[234:237], v[96:99]
	v_mfma_f32_16x16x32_bf16 v[92:95], v[144:147], v[234:237], v[92:95]
	v_mfma_f32_16x16x32_bf16 v[80:83], v[136:139], v[242:245], v[80:83]
	v_mfma_f32_16x16x32_bf16 v[76:79], v[144:147], v[242:245], v[76:79]
	v_mfma_f32_16x16x32_bf16 v[120:123], v[148:151], v[176:179], v[120:123]
	v_mfma_f32_16x16x32_bf16 v[116:119], v[168:171], v[176:179], v[116:119]
	v_mfma_f32_16x16x32_bf16 v[104:107], v[148:151], v[184:187], v[104:107]
	v_mfma_f32_16x16x32_bf16 v[100:103], v[168:171], v[184:187], v[100:103]
	v_mfma_f32_16x16x32_bf16 v[88:91], v[148:151], v[210:213], v[88:91]
	v_mfma_f32_16x16x32_bf16 v[84:87], v[168:171], v[210:213], v[84:87]
	v_mfma_f32_16x16x32_bf16 v[72:75], v[148:151], v[238:241], v[72:75]
	v_mfma_f32_16x16x32_bf16 v[68:71], v[168:171], v[238:241], v[68:71]
	v_mfma_f32_16x16x32_bf16 v[120:123], v[152:155], v[180:183], v[120:123]
	v_mfma_f32_16x16x32_bf16 v[116:119], v[172:175], v[180:183], v[116:119]
	v_mfma_f32_16x16x32_bf16 v[104:107], v[152:155], v[192:195], v[104:107]
	v_mfma_f32_16x16x32_bf16 v[100:103], v[172:175], v[192:195], v[100:103]
	v_mfma_f32_16x16x32_bf16 v[88:91], v[152:155], v[234:237], v[88:91]
	v_mfma_f32_16x16x32_bf16 v[84:87], v[172:175], v[234:237], v[84:87]
	v_mfma_f32_16x16x32_bf16 v[72:75], v[152:155], v[242:245], v[72:75]
	v_mfma_f32_16x16x32_bf16 v[68:71], v[172:175], v[242:245], v[68:71]
	s_barrier
	s_add_i32 s34, s34, s0
	s_mov_b32 m0, s34
	ds_read_b128 v[176:179], v189 offset:16384
	ds_read_b128 v[180:183], v189 offset:17408
	ds_read_b128 v[184:187], v189 offset:18432
	ds_read_b128 v[192:195], v189 offset:19456
	ds_read_b128 v[210:213], v189 offset:20480
	ds_read_b128 v[234:237], v189 offset:21504
	ds_read_b128 v[238:241], v189 offset:22528
	ds_read_b128 v[242:245], v189 offset:23552
	global_load_lds_dwordx4 v156, s[64:65]
	s_add_i32 m0, s34, 0x2000
	s_add_u32 s34, s64, 0x4000
	s_addc_u32 s35, s65, 0
	s_add_i32 s55, s55, s0
	global_load_lds_dwordx4 v160, s[64:65]
	s_mov_b32 m0, s55
	s_nop 0
	global_load_lds_dwordx4 v156, s[34:35]
	s_add_i32 m0, s55, 0x2000
	s_nop 0
	global_load_lds_dwordx4 v160, s[34:35]
	s_mov_b32 m0, s29
	s_nop 0
	global_load_lds_dwordx4 v158, s[66:67]
	s_mov_b32 m0, s45
	s_nop 0
	global_load_lds_dwordx4 v162, s[66:67]
	s_waitcnt vmcnt(8) lgkmcnt(0)
	s_barrier
	v_mfma_f32_16x16x32_bf16 v[64:67], v[132:135], v[176:179], v[64:67]
	v_mfma_f32_16x16x32_bf16 v[60:63], v[140:143], v[176:179], v[60:63]
	v_mfma_f32_16x16x32_bf16 v[48:51], v[132:135], v[184:187], v[48:51]
	v_mfma_f32_16x16x32_bf16 v[44:47], v[140:143], v[184:187], v[44:47]
	v_mfma_f32_16x16x32_bf16 v[30:33], v[132:135], v[210:213], v[30:33]
	v_mfma_f32_16x16x32_bf16 v[26:29], v[140:143], v[210:213], v[26:29]
	v_mfma_f32_16x16x32_bf16 v[14:17], v[132:135], v[238:241], v[14:17]
	v_mfma_f32_16x16x32_bf16 v[10:13], v[140:143], v[238:241], v[10:13]
	v_mfma_f32_16x16x32_bf16 v[64:67], v[136:139], v[180:183], v[64:67]
	v_mfma_f32_16x16x32_bf16 v[60:63], v[144:147], v[180:183], v[60:63]
	v_mfma_f32_16x16x32_bf16 v[48:51], v[136:139], v[192:195], v[48:51]
	v_mfma_f32_16x16x32_bf16 v[44:47], v[144:147], v[192:195], v[44:47]
	v_mfma_f32_16x16x32_bf16 v[30:33], v[136:139], v[234:237], v[30:33]
	v_mfma_f32_16x16x32_bf16 v[26:29], v[144:147], v[234:237], v[26:29]
	v_mfma_f32_16x16x32_bf16 v[14:17], v[136:139], v[242:245], v[14:17]
	v_mfma_f32_16x16x32_bf16 v[10:13], v[144:147], v[242:245], v[10:13]
	v_mfma_f32_16x16x32_bf16 v[56:59], v[148:151], v[176:179], v[56:59]
	v_mfma_f32_16x16x32_bf16 v[52:55], v[168:171], v[176:179], v[52:55]
	v_mfma_f32_16x16x32_bf16 v[40:43], v[148:151], v[184:187], v[40:43]
	v_mfma_f32_16x16x32_bf16 v[36:39], v[168:171], v[184:187], v[36:39]
	v_mfma_f32_16x16x32_bf16 v[22:25], v[148:151], v[210:213], v[22:25]
	v_mfma_f32_16x16x32_bf16 v[18:21], v[168:171], v[210:213], v[18:21]
	v_mfma_f32_16x16x32_bf16 v[6:9], v[148:151], v[238:241], v[6:9]
	v_mfma_f32_16x16x32_bf16 v[2:5], v[168:171], v[238:241], v[2:5]
	v_mfma_f32_16x16x32_bf16 v[56:59], v[152:155], v[180:183], v[56:59]
	v_mfma_f32_16x16x32_bf16 v[52:55], v[172:175], v[180:183], v[52:55]
	v_mfma_f32_16x16x32_bf16 v[40:43], v[152:155], v[192:195], v[40:43]
	v_mfma_f32_16x16x32_bf16 v[36:39], v[172:175], v[192:195], v[36:39]
	v_mfma_f32_16x16x32_bf16 v[22:25], v[152:155], v[234:237], v[22:25]
	v_mfma_f32_16x16x32_bf16 v[18:21], v[172:175], v[234:237], v[18:21]
	v_mfma_f32_16x16x32_bf16 v[6:9], v[152:155], v[242:245], v[6:9]
	v_mfma_f32_16x16x32_bf16 v[2:5], v[172:175], v[242:245], v[2:5]
	s_barrier
	s_add_i32 s55, 0, 0x18000
	s_add_i32 s58, 0, 0x1c000
	ds_read_b128 v[132:135], v190 offset:32768
	ds_read_b128 v[136:139], v190 offset:33792
	ds_read_b128 v[140:143], v190 offset:34816
	ds_read_b128 v[144:147], v190 offset:35840
	ds_read_b128 v[148:151], v190 offset:49152
	ds_read_b128 v[152:155], v190 offset:50176
	ds_read_b128 v[168:171], v190 offset:51200
	ds_read_b128 v[172:175], v190 offset:52224
	s_add_u32 s34, s66, 0x100000
	s_addc_u32 s35, s67, 0
	s_mov_b32 m0, s82
	ds_read_b128 v[176:179], v189 offset:32768
	ds_read_b128 v[180:183], v189 offset:33792
	ds_read_b128 v[184:187], v189 offset:34816
	ds_read_b128 v[192:195], v189 offset:35840
	ds_read_b128 v[210:213], v189 offset:36864
	ds_read_b128 v[234:237], v189 offset:37888
	ds_read_b128 v[238:241], v189 offset:38912
	ds_read_b128 v[242:245], v189 offset:39936
	global_load_lds_dwordx4 v158, s[34:35]
	s_mov_b32 m0, s90
	s_nop 0
	global_load_lds_dwordx4 v162, s[34:35]
	s_waitcnt vmcnt(8) lgkmcnt(0)
	s_barrier
	v_mfma_f32_16x16x32_bf16 v[128:131], v[132:135], v[176:179], v[128:131]
	v_mfma_f32_16x16x32_bf16 v[124:127], v[140:143], v[176:179], v[124:127]
	v_mfma_f32_16x16x32_bf16 v[112:115], v[132:135], v[184:187], v[112:115]
	v_mfma_f32_16x16x32_bf16 v[108:111], v[140:143], v[184:187], v[108:111]
	v_mfma_f32_16x16x32_bf16 v[96:99], v[132:135], v[210:213], v[96:99]
	v_mfma_f32_16x16x32_bf16 v[92:95], v[140:143], v[210:213], v[92:95]
	v_mfma_f32_16x16x32_bf16 v[80:83], v[132:135], v[238:241], v[80:83]
	v_mfma_f32_16x16x32_bf16 v[76:79], v[140:143], v[238:241], v[76:79]
	v_mfma_f32_16x16x32_bf16 v[128:131], v[136:139], v[180:183], v[128:131]
	v_mfma_f32_16x16x32_bf16 v[124:127], v[144:147], v[180:183], v[124:127]
	v_mfma_f32_16x16x32_bf16 v[112:115], v[136:139], v[192:195], v[112:115]
	v_mfma_f32_16x16x32_bf16 v[108:111], v[144:147], v[192:195], v[108:111]
	v_mfma_f32_16x16x32_bf16 v[96:99], v[136:139], v[234:237], v[96:99]
	v_mfma_f32_16x16x32_bf16 v[92:95], v[144:147], v[234:237], v[92:95]
	v_mfma_f32_16x16x32_bf16 v[80:83], v[136:139], v[242:245], v[80:83]
	v_mfma_f32_16x16x32_bf16 v[76:79], v[144:147], v[242:245], v[76:79]
	v_mfma_f32_16x16x32_bf16 v[120:123], v[148:151], v[176:179], v[120:123]
	v_mfma_f32_16x16x32_bf16 v[116:119], v[168:171], v[176:179], v[116:119]
	v_mfma_f32_16x16x32_bf16 v[104:107], v[148:151], v[184:187], v[104:107]
	v_mfma_f32_16x16x32_bf16 v[100:103], v[168:171], v[184:187], v[100:103]
	v_mfma_f32_16x16x32_bf16 v[88:91], v[148:151], v[210:213], v[88:91]
	v_mfma_f32_16x16x32_bf16 v[84:87], v[168:171], v[210:213], v[84:87]
	v_mfma_f32_16x16x32_bf16 v[72:75], v[148:151], v[238:241], v[72:75]
	v_mfma_f32_16x16x32_bf16 v[68:71], v[168:171], v[238:241], v[68:71]
	v_mfma_f32_16x16x32_bf16 v[120:123], v[152:155], v[180:183], v[120:123]
	v_mfma_f32_16x16x32_bf16 v[116:119], v[172:175], v[180:183], v[116:119]
	v_mfma_f32_16x16x32_bf16 v[104:107], v[152:155], v[192:195], v[104:107]
	v_mfma_f32_16x16x32_bf16 v[100:103], v[172:175], v[192:195], v[100:103]
	v_mfma_f32_16x16x32_bf16 v[88:91], v[152:155], v[234:237], v[88:91]
	v_mfma_f32_16x16x32_bf16 v[84:87], v[172:175], v[234:237], v[84:87]
	v_mfma_f32_16x16x32_bf16 v[72:75], v[152:155], v[242:245], v[72:75]
	v_mfma_f32_16x16x32_bf16 v[68:71], v[172:175], v[242:245], v[68:71]
	s_barrier
	s_add_u32 s34, s64, 0x8000
	s_addc_u32 s35, s65, 0
	s_add_i32 s55, s55, s0
	s_mov_b32 m0, s55
	ds_read_b128 v[176:179], v189 offset:49152
	ds_read_b128 v[180:183], v189 offset:50176
	ds_read_b128 v[184:187], v189 offset:51200
	ds_read_b128 v[192:195], v189 offset:52224
	ds_read_b128 v[210:213], v189 offset:53248
	ds_read_b128 v[234:237], v189 offset:54272
	ds_read_b128 v[238:241], v189 offset:55296
	ds_read_b128 v[242:245], v189 offset:56320
	global_load_lds_dwordx4 v156, s[34:35]
	s_add_i32 m0, s55, 0x2000
	v_lshl_add_u64 v[250:251], s[34:35], 0, v[160:161]
	s_add_u32 s34, s64, 0xc000
	s_addc_u32 s35, s65, 0
	s_add_i32 s55, s58, s0
	global_load_lds_dwordx4 v[250:251], off
	s_mov_b32 m0, s55
	s_nop 0
	global_load_lds_dwordx4 v156, s[34:35]
	s_add_i32 m0, s55, 0x2000
	s_nop 0
	global_load_lds_dwordx4 v160, s[34:35]
	s_mov_b32 m0, s91
	s_nop 0
	s_add_u32 s100, s66, s92
	s_addc_u32 s101, s67, s93
	global_load_lds_dwordx4 v158, s[100:101]
	s_mov_b32 m0, s30
	s_nop 0
	s_add_u32 s100, s66, s92
	s_addc_u32 s101, s67, s93
	global_load_lds_dwordx4 v162, s[100:101]
	s_waitcnt vmcnt(8) lgkmcnt(0)
	s_barrier
	v_mfma_f32_16x16x32_bf16 v[64:67], v[132:135], v[176:179], v[64:67]
	v_mfma_f32_16x16x32_bf16 v[60:63], v[140:143], v[176:179], v[60:63]
	v_mfma_f32_16x16x32_bf16 v[48:51], v[132:135], v[184:187], v[48:51]
	v_mfma_f32_16x16x32_bf16 v[44:47], v[140:143], v[184:187], v[44:47]
	v_mfma_f32_16x16x32_bf16 v[30:33], v[132:135], v[210:213], v[30:33]
	v_mfma_f32_16x16x32_bf16 v[26:29], v[140:143], v[210:213], v[26:29]
	v_mfma_f32_16x16x32_bf16 v[14:17], v[132:135], v[238:241], v[14:17]
	v_mfma_f32_16x16x32_bf16 v[10:13], v[140:143], v[238:241], v[10:13]
	v_mfma_f32_16x16x32_bf16 v[64:67], v[136:139], v[180:183], v[64:67]
	v_mfma_f32_16x16x32_bf16 v[60:63], v[144:147], v[180:183], v[60:63]
	v_mfma_f32_16x16x32_bf16 v[48:51], v[136:139], v[192:195], v[48:51]
	v_mfma_f32_16x16x32_bf16 v[44:47], v[144:147], v[192:195], v[44:47]
	v_mfma_f32_16x16x32_bf16 v[30:33], v[136:139], v[234:237], v[30:33]
	v_mfma_f32_16x16x32_bf16 v[26:29], v[144:147], v[234:237], v[26:29]
	v_mfma_f32_16x16x32_bf16 v[14:17], v[136:139], v[242:245], v[14:17]
	v_mfma_f32_16x16x32_bf16 v[10:13], v[144:147], v[242:245], v[10:13]
	v_mfma_f32_16x16x32_bf16 v[56:59], v[148:151], v[176:179], v[56:59]
	v_mfma_f32_16x16x32_bf16 v[52:55], v[168:171], v[176:179], v[52:55]
	v_mfma_f32_16x16x32_bf16 v[40:43], v[148:151], v[184:187], v[40:43]
	v_mfma_f32_16x16x32_bf16 v[36:39], v[168:171], v[184:187], v[36:39]
	v_mfma_f32_16x16x32_bf16 v[22:25], v[148:151], v[210:213], v[22:25]
	v_mfma_f32_16x16x32_bf16 v[18:21], v[168:171], v[210:213], v[18:21]
	v_mfma_f32_16x16x32_bf16 v[6:9], v[148:151], v[238:241], v[6:9]
	v_mfma_f32_16x16x32_bf16 v[2:5], v[168:171], v[238:241], v[2:5]
	v_mfma_f32_16x16x32_bf16 v[56:59], v[152:155], v[180:183], v[56:59]
	v_mfma_f32_16x16x32_bf16 v[52:55], v[172:175], v[180:183], v[52:55]
	v_mfma_f32_16x16x32_bf16 v[40:43], v[152:155], v[192:195], v[40:43]
	v_mfma_f32_16x16x32_bf16 v[36:39], v[172:175], v[192:195], v[36:39]
	v_mfma_f32_16x16x32_bf16 v[22:25], v[152:155], v[234:237], v[22:25]
	v_mfma_f32_16x16x32_bf16 v[18:21], v[172:175], v[234:237], v[18:21]
	v_mfma_f32_16x16x32_bf16 v[6:9], v[152:155], v[242:245], v[6:9]
	v_mfma_f32_16x16x32_bf16 v[2:5], v[172:175], v[242:245], v[2:5]
	s_barrier
	s_add_i32 s49, s49, 2
	s_add_u32 s13, s13, 0x10000
	s_addc_u32 s28, s28, 0
	s_cmp_gt_u32 s49, 61
	s_mov_b64 s[60:61], s[62:63]
	s_cbranch_scc0 .LBB0_877
	s_and_b64 vcc, exec, s[46:47]
	s_cbranch_vccz .LBB0_880
	s_barrier

.LBB0_1069:
	s_add_u32 s28, s64, 0x10000
	s_addc_u32 s58, s65, 0
	s_add_u32 s12, s12, 0x100080
	v_mov_b32_e32 v36, 0
	s_addc_u32 s13, s13, 0
	s_mov_b32 s59, -2
	v_mov_b32_e32 v37, v36
	v_mov_b32_e32 v38, v36
	v_mov_b32_e32 v39, v36
	v_mov_b32_e32 v44, v36
	v_mov_b32_e32 v45, v36
	v_mov_b32_e32 v46, v36
	v_mov_b32_e32 v47, v36
	v_mov_b32_e32 v52, v36
	v_mov_b32_e32 v53, v36
	v_mov_b32_e32 v54, v36
	v_mov_b32_e32 v55, v36
	v_mov_b32_e32 v60, v36
	v_mov_b32_e32 v61, v36
	v_mov_b32_e32 v62, v36
	v_mov_b32_e32 v63, v36
	v_mov_b32_e32 v68, v36
	v_mov_b32_e32 v69, v36
	v_mov_b32_e32 v70, v36
	v_mov_b32_e32 v71, v36
	v_mov_b32_e32 v76, v36
	v_mov_b32_e32 v77, v36
	v_mov_b32_e32 v78, v36
	v_mov_b32_e32 v79, v36
	v_mov_b32_e32 v84, v36
	v_mov_b32_e32 v85, v36
	v_mov_b32_e32 v86, v36
	v_mov_b32_e32 v87, v36
	v_mov_b32_e32 v92, v36
	v_mov_b32_e32 v93, v36
	v_mov_b32_e32 v94, v36
	v_mov_b32_e32 v95, v36
	v_mov_b32_e32 v40, v36
	v_mov_b32_e32 v41, v36
	v_mov_b32_e32 v42, v36
	v_mov_b32_e32 v43, v36
	v_mov_b32_e32 v48, v36
	v_mov_b32_e32 v49, v36
	v_mov_b32_e32 v50, v36
	v_mov_b32_e32 v51, v36
	v_mov_b32_e32 v56, v36
	v_mov_b32_e32 v57, v36
	v_mov_b32_e32 v58, v36
	v_mov_b32_e32 v59, v36
	v_mov_b32_e32 v64, v36
	v_mov_b32_e32 v65, v36
	v_mov_b32_e32 v66, v36
	v_mov_b32_e32 v67, v36
	v_mov_b32_e32 v72, v36
	v_mov_b32_e32 v73, v36
	v_mov_b32_e32 v74, v36
	v_mov_b32_e32 v75, v36
	v_mov_b32_e32 v80, v36
	v_mov_b32_e32 v81, v36
	v_mov_b32_e32 v82, v36
	v_mov_b32_e32 v83, v36
	v_mov_b32_e32 v88, v36
	v_mov_b32_e32 v89, v36
	v_mov_b32_e32 v90, v36
	v_mov_b32_e32 v91, v36
	v_mov_b32_e32 v96, v36
	v_mov_b32_e32 v97, v36
	v_mov_b32_e32 v98, v36
	v_mov_b32_e32 v99, v36
	v_mov_b32_e32 v104, v36
	v_mov_b32_e32 v105, v36
	v_mov_b32_e32 v106, v36
	v_mov_b32_e32 v107, v36
	v_mov_b32_e32 v116, v36
	v_mov_b32_e32 v117, v36
	v_mov_b32_e32 v118, v36
	v_mov_b32_e32 v119, v36
	v_mov_b32_e32 v124, v36
	v_mov_b32_e32 v125, v36
	v_mov_b32_e32 v126, v36
	v_mov_b32_e32 v127, v36
	v_mov_b32_e32 v132, v36
	v_mov_b32_e32 v133, v36
	v_mov_b32_e32 v134, v36
	v_mov_b32_e32 v135, v36
	v_mov_b32_e32 v140, v36
	v_mov_b32_e32 v141, v36
	v_mov_b32_e32 v142, v36
	v_mov_b32_e32 v143, v36
	v_mov_b32_e32 v148, v36
	v_mov_b32_e32 v149, v36
	v_mov_b32_e32 v150, v36
	v_mov_b32_e32 v151, v36
	v_mov_b32_e32 v156, v36
	v_mov_b32_e32 v157, v36
	v_mov_b32_e32 v158, v36
	v_mov_b32_e32 v159, v36
	v_mov_b32_e32 v164, v36
	v_mov_b32_e32 v165, v36
	v_mov_b32_e32 v166, v36
	v_mov_b32_e32 v167, v36
	v_mov_b32_e32 v108, v36
	v_mov_b32_e32 v109, v36
	v_mov_b32_e32 v110, v36
	v_mov_b32_e32 v111, v36
	v_mov_b32_e32 v120, v36
	v_mov_b32_e32 v121, v36
	v_mov_b32_e32 v122, v36
	v_mov_b32_e32 v123, v36
	v_mov_b32_e32 v128, v36
	v_mov_b32_e32 v129, v36
	v_mov_b32_e32 v130, v36
	v_mov_b32_e32 v131, v36
	v_mov_b32_e32 v136, v36
	v_mov_b32_e32 v137, v36
	v_mov_b32_e32 v138, v36
	v_mov_b32_e32 v139, v36
	v_mov_b32_e32 v144, v36
	v_mov_b32_e32 v145, v36
	v_mov_b32_e32 v146, v36
	v_mov_b32_e32 v147, v36
	v_mov_b32_e32 v152, v36
	v_mov_b32_e32 v153, v36
	v_mov_b32_e32 v154, v36
	v_mov_b32_e32 v155, v36
	v_mov_b32_e32 v160, v36
	v_mov_b32_e32 v161, v36
	v_mov_b32_e32 v162, v36
	v_mov_b32_e32 v163, v36
	v_mov_b32_e32 v168, v36
	v_mov_b32_e32 v169, v36
	v_mov_b32_e32 v170, v36
	v_mov_b32_e32 v171, v36
	v_add_u32_e32 v2, 0x10000, v196
.LBB0_1070:
	s_add_u32 s34, s12, 0xfff00080
	s_addc_u32 s35, s13, -1
	s_add_i32 s48, 0, 0x10000
	s_cmp_eq_u32 s59, 28
	s_cselect_b32 s67, s61, s35
	s_cselect_b32 s66, s60, s34
	s_cselect_b32 s65, s63, s58
	s_cselect_b32 s64, s62, s28
	s_add_i32 s49, 0, 0x14000
	ds_read_b128 v[100:103], v2 offset:0
	ds_read_b128 v[112:115], v2 offset:1024
	ds_read_b128 v[172:175], v2 offset:2048
	ds_read_b128 v[188:191], v2 offset:3072
	ds_read_b128 v[192:195], v2 offset:16384
	ds_read_b128 v[200:203], v2 offset:17408
	ds_read_b128 v[204:207], v2 offset:18432
	ds_read_b128 v[210:213], v2 offset:19456
	s_add_i32 m0, s29, 0xc000
	ds_read_b128 v[216:219], v197
	ds_read_b128 v[220:223], v197 offset:1024
	ds_read_b128 v[224:227], v197 offset:2048
	ds_read_b128 v[228:231], v197 offset:3072
	ds_read_b128 v[232:235], v197 offset:4096
	ds_read_b128 v[236:239], v197 offset:5120
	ds_read_b128 v[240:243], v197 offset:6144
	ds_read_b128 v[244:247], v197 offset:7168
	global_load_lds_dwordx4 v184, s[12:13]
	s_add_i32 m0, s29, 0xe000
	s_nop 0
	global_load_lds_dwordx4 v186, s[12:13]
	s_waitcnt vmcnt(8) lgkmcnt(0)
	s_barrier
	v_mfma_i32_16x16x64_i8 v[168:171], v[100:103], v[216:219], v[168:171]
	v_mfma_i32_16x16x64_i8 v[160:163], v[172:175], v[216:219], v[160:163]
	v_mfma_i32_16x16x64_i8 v[152:155], v[100:103], v[224:227], v[152:155]
	v_mfma_i32_16x16x64_i8 v[144:147], v[172:175], v[224:227], v[144:147]
	v_mfma_i32_16x16x64_i8 v[136:139], v[100:103], v[232:235], v[136:139]
	v_mfma_i32_16x16x64_i8 v[128:131], v[172:175], v[232:235], v[128:131]
	v_mfma_i32_16x16x64_i8 v[120:123], v[100:103], v[240:243], v[120:123]
	v_mfma_i32_16x16x64_i8 v[108:111], v[172:175], v[240:243], v[108:111]
	v_mfma_i32_16x16x64_i8 v[168:171], v[112:115], v[220:223], v[168:171]
	v_mfma_i32_16x16x64_i8 v[160:163], v[188:191], v[220:223], v[160:163]
	v_mfma_i32_16x16x64_i8 v[152:155], v[112:115], v[228:231], v[152:155]
	v_mfma_i32_16x16x64_i8 v[144:147], v[188:191], v[228:231], v[144:147]
	v_mfma_i32_16x16x64_i8 v[136:139], v[112:115], v[236:239], v[136:139]
	v_mfma_i32_16x16x64_i8 v[128:131], v[188:191], v[236:239], v[128:131]
	v_mfma_i32_16x16x64_i8 v[120:123], v[112:115], v[244:247], v[120:123]
	v_mfma_i32_16x16x64_i8 v[108:111], v[188:191], v[244:247], v[108:111]
	v_mfma_i32_16x16x64_i8 v[164:167], v[192:195], v[216:219], v[164:167]
	v_mfma_i32_16x16x64_i8 v[156:159], v[204:207], v[216:219], v[156:159]
	v_mfma_i32_16x16x64_i8 v[148:151], v[192:195], v[224:227], v[148:151]
	v_mfma_i32_16x16x64_i8 v[140:143], v[204:207], v[224:227], v[140:143]
	v_mfma_i32_16x16x64_i8 v[132:135], v[192:195], v[232:235], v[132:135]
	v_mfma_i32_16x16x64_i8 v[124:127], v[204:207], v[232:235], v[124:127]
	v_mfma_i32_16x16x64_i8 v[116:119], v[192:195], v[240:243], v[116:119]
	v_mfma_i32_16x16x64_i8 v[104:107], v[204:207], v[240:243], v[104:107]
	v_mfma_i32_16x16x64_i8 v[164:167], v[200:203], v[220:223], v[164:167]
	v_mfma_i32_16x16x64_i8 v[156:159], v[210:213], v[220:223], v[156:159]
	v_mfma_i32_16x16x64_i8 v[148:151], v[200:203], v[228:231], v[148:151]
	v_mfma_i32_16x16x64_i8 v[140:143], v[210:213], v[228:231], v[140:143]
	v_mfma_i32_16x16x64_i8 v[132:135], v[200:203], v[236:239], v[132:135]
	v_mfma_i32_16x16x64_i8 v[124:127], v[210:213], v[236:239], v[124:127]
	v_mfma_i32_16x16x64_i8 v[116:119], v[200:203], v[244:247], v[116:119]
	v_mfma_i32_16x16x64_i8 v[104:107], v[210:213], v[244:247], v[104:107]
	s_barrier
	s_add_i32 s34, s48, s0
	s_mov_b32 m0, s34
	ds_read_b128 v[216:219], v197 offset:16384
	ds_read_b128 v[220:223], v197 offset:17408
	ds_read_b128 v[224:227], v197 offset:18432
	ds_read_b128 v[228:231], v197 offset:19456
	ds_read_b128 v[232:235], v197 offset:20480
	ds_read_b128 v[236:239], v197 offset:21504
	ds_read_b128 v[240:243], v197 offset:22528
	ds_read_b128 v[244:247], v197 offset:23552
	global_load_lds_dwordx4 v176, s[64:65]
	s_add_i32 m0, s34, 0x2000
	s_add_u32 s34, s64, 0x4000
	s_addc_u32 s35, s65, 0
	s_add_i32 s48, s49, s0
	global_load_lds_dwordx4 v180, s[64:65]
	s_mov_b32 m0, s48
	s_nop 0
	global_load_lds_dwordx4 v176, s[34:35]
	s_add_i32 m0, s48, 0x2000
	s_nop 0
	global_load_lds_dwordx4 v180, s[34:35]
	s_mov_b32 m0, s29
	s_nop 0
	global_load_lds_dwordx4 v178, s[66:67]
	s_mov_b32 m0, s45
	s_nop 0
	global_load_lds_dwordx4 v182, s[66:67]
	s_waitcnt vmcnt(8) lgkmcnt(0)
	s_barrier
	v_mfma_i32_16x16x64_i8 v[96:99], v[100:103], v[216:219], v[96:99]
	v_mfma_i32_16x16x64_i8 v[88:91], v[172:175], v[216:219], v[88:91]
	v_mfma_i32_16x16x64_i8 v[80:83], v[100:103], v[224:227], v[80:83]
	v_mfma_i32_16x16x64_i8 v[72:75], v[172:175], v[224:227], v[72:75]
	v_mfma_i32_16x16x64_i8 v[64:67], v[100:103], v[232:235], v[64:67]
	v_mfma_i32_16x16x64_i8 v[56:59], v[172:175], v[232:235], v[56:59]
	v_mfma_i32_16x16x64_i8 v[48:51], v[100:103], v[240:243], v[48:51]
	v_mfma_i32_16x16x64_i8 v[40:43], v[172:175], v[240:243], v[40:43]
	v_mfma_i32_16x16x64_i8 v[96:99], v[112:115], v[220:223], v[96:99]
	v_mfma_i32_16x16x64_i8 v[88:91], v[188:191], v[220:223], v[88:91]
	v_mfma_i32_16x16x64_i8 v[80:83], v[112:115], v[228:231], v[80:83]
	v_mfma_i32_16x16x64_i8 v[72:75], v[188:191], v[228:231], v[72:75]
	v_mfma_i32_16x16x64_i8 v[64:67], v[112:115], v[236:239], v[64:67]
	v_mfma_i32_16x16x64_i8 v[56:59], v[188:191], v[236:239], v[56:59]
	v_mfma_i32_16x16x64_i8 v[48:51], v[112:115], v[244:247], v[48:51]
	v_mfma_i32_16x16x64_i8 v[40:43], v[188:191], v[244:247], v[40:43]
	v_mfma_i32_16x16x64_i8 v[92:95], v[192:195], v[216:219], v[92:95]
	v_mfma_i32_16x16x64_i8 v[84:87], v[204:207], v[216:219], v[84:87]
	v_mfma_i32_16x16x64_i8 v[76:79], v[192:195], v[224:227], v[76:79]
	v_mfma_i32_16x16x64_i8 v[68:71], v[204:207], v[224:227], v[68:71]
	v_mfma_i32_16x16x64_i8 v[60:63], v[192:195], v[232:235], v[60:63]
	v_mfma_i32_16x16x64_i8 v[52:55], v[204:207], v[232:235], v[52:55]
	v_mfma_i32_16x16x64_i8 v[44:47], v[192:195], v[240:243], v[44:47]
	v_mfma_i32_16x16x64_i8 v[36:39], v[204:207], v[240:243], v[36:39]
	v_mfma_i32_16x16x64_i8 v[92:95], v[200:203], v[220:223], v[92:95]
	v_mfma_i32_16x16x64_i8 v[84:87], v[210:213], v[220:223], v[84:87]
	v_mfma_i32_16x16x64_i8 v[76:79], v[200:203], v[228:231], v[76:79]
	v_mfma_i32_16x16x64_i8 v[68:71], v[210:213], v[228:231], v[68:71]
	v_mfma_i32_16x16x64_i8 v[60:63], v[200:203], v[236:239], v[60:63]
	v_mfma_i32_16x16x64_i8 v[52:55], v[210:213], v[236:239], v[52:55]
	v_mfma_i32_16x16x64_i8 v[44:47], v[200:203], v[244:247], v[44:47]
	v_mfma_i32_16x16x64_i8 v[36:39], v[210:213], v[244:247], v[36:39]
	s_barrier
	s_add_i32 s48, 0, 0x18000
	s_add_i32 s49, 0, 0x1c000
	ds_read_b128 v[100:103], v2 offset:32768
	ds_read_b128 v[112:115], v2 offset:33792
	ds_read_b128 v[172:175], v2 offset:34816
	ds_read_b128 v[188:191], v2 offset:35840
	ds_read_b128 v[192:195], v2 offset:49152
	ds_read_b128 v[200:203], v2 offset:50176
	ds_read_b128 v[204:207], v2 offset:51200
	ds_read_b128 v[210:213], v2 offset:52224
	s_add_u32 s34, s66, 0x100000
	s_addc_u32 s35, s67, 0
	s_mov_b32 m0, s82
	ds_read_b128 v[216:219], v197 offset:32768
	ds_read_b128 v[220:223], v197 offset:33792
	ds_read_b128 v[224:227], v197 offset:34816
	ds_read_b128 v[228:231], v197 offset:35840
	ds_read_b128 v[232:235], v197 offset:36864
	ds_read_b128 v[236:239], v197 offset:37888
	ds_read_b128 v[240:243], v197 offset:38912
	ds_read_b128 v[244:247], v197 offset:39936
	global_load_lds_dwordx4 v178, s[34:35]
	s_mov_b32 m0, s90
	s_nop 0
	global_load_lds_dwordx4 v182, s[34:35]
	s_waitcnt vmcnt(8) lgkmcnt(0)
	s_barrier
	v_mfma_i32_16x16x64_i8 v[168:171], v[100:103], v[216:219], v[168:171]
	v_mfma_i32_16x16x64_i8 v[160:163], v[172:175], v[216:219], v[160:163]
	v_mfma_i32_16x16x64_i8 v[152:155], v[100:103], v[224:227], v[152:155]
	v_mfma_i32_16x16x64_i8 v[144:147], v[172:175], v[224:227], v[144:147]
	v_mfma_i32_16x16x64_i8 v[136:139], v[100:103], v[232:235], v[136:139]
	v_mfma_i32_16x16x64_i8 v[128:131], v[172:175], v[232:235], v[128:131]
	v_mfma_i32_16x16x64_i8 v[120:123], v[100:103], v[240:243], v[120:123]
	v_mfma_i32_16x16x64_i8 v[108:111], v[172:175], v[240:243], v[108:111]
	v_mfma_i32_16x16x64_i8 v[168:171], v[112:115], v[220:223], v[168:171]
	v_mfma_i32_16x16x64_i8 v[160:163], v[188:191], v[220:223], v[160:163]
	v_mfma_i32_16x16x64_i8 v[152:155], v[112:115], v[228:231], v[152:155]
	v_mfma_i32_16x16x64_i8 v[144:147], v[188:191], v[228:231], v[144:147]
	v_mfma_i32_16x16x64_i8 v[136:139], v[112:115], v[236:239], v[136:139]
	v_mfma_i32_16x16x64_i8 v[128:131], v[188:191], v[236:239], v[128:131]
	v_mfma_i32_16x16x64_i8 v[120:123], v[112:115], v[244:247], v[120:123]
	v_mfma_i32_16x16x64_i8 v[108:111], v[188:191], v[244:247], v[108:111]
	v_mfma_i32_16x16x64_i8 v[164:167], v[192:195], v[216:219], v[164:167]
	v_mfma_i32_16x16x64_i8 v[156:159], v[204:207], v[216:219], v[156:159]
	v_mfma_i32_16x16x64_i8 v[148:151], v[192:195], v[224:227], v[148:151]
	v_mfma_i32_16x16x64_i8 v[140:143], v[204:207], v[224:227], v[140:143]
	v_mfma_i32_16x16x64_i8 v[132:135], v[192:195], v[232:235], v[132:135]
	v_mfma_i32_16x16x64_i8 v[124:127], v[204:207], v[232:235], v[124:127]
	v_mfma_i32_16x16x64_i8 v[116:119], v[192:195], v[240:243], v[116:119]
	v_mfma_i32_16x16x64_i8 v[104:107], v[204:207], v[240:243], v[104:107]
	v_mfma_i32_16x16x64_i8 v[164:167], v[200:203], v[220:223], v[164:167]
	v_mfma_i32_16x16x64_i8 v[156:159], v[210:213], v[220:223], v[156:159]
	v_mfma_i32_16x16x64_i8 v[148:151], v[200:203], v[228:231], v[148:151]
	v_mfma_i32_16x16x64_i8 v[140:143], v[210:213], v[228:231], v[140:143]
	v_mfma_i32_16x16x64_i8 v[132:135], v[200:203], v[236:239], v[132:135]
	v_mfma_i32_16x16x64_i8 v[124:127], v[210:213], v[236:239], v[124:127]
	v_mfma_i32_16x16x64_i8 v[116:119], v[200:203], v[244:247], v[116:119]
	v_mfma_i32_16x16x64_i8 v[104:107], v[210:213], v[244:247], v[104:107]
	s_barrier
	s_add_u32 s34, s64, 0x8000
	s_addc_u32 s35, s65, 0
	s_add_i32 s48, s48, s0
	s_mov_b32 m0, s48
	ds_read_b128 v[216:219], v197 offset:49152
	ds_read_b128 v[220:223], v197 offset:50176
	ds_read_b128 v[224:227], v197 offset:51200
	ds_read_b128 v[228:231], v197 offset:52224
	ds_read_b128 v[232:235], v197 offset:53248
	ds_read_b128 v[236:239], v197 offset:54272
	ds_read_b128 v[240:243], v197 offset:55296
	ds_read_b128 v[244:247], v197 offset:56320
	global_load_lds_dwordx4 v176, s[34:35]
	s_add_i32 m0, s48, 0x2000
	v_lshl_add_u64 v[252:253], s[34:35], 0, v[180:181]
	s_add_u32 s34, s64, 0xc000
	s_addc_u32 s35, s65, 0
	s_add_i32 s48, s49, s0
	global_load_lds_dwordx4 v[252:253], off
	s_mov_b32 m0, s48
	s_nop 0
	global_load_lds_dwordx4 v176, s[34:35]
	s_add_i32 m0, s48, 0x2000
	s_nop 0
	global_load_lds_dwordx4 v180, s[34:35]
	s_mov_b32 m0, s91
	s_nop 0
	s_add_u32 s100, s66, s92
	s_addc_u32 s101, s67, s93
	global_load_lds_dwordx4 v178, s[100:101]
	s_mov_b32 m0, s30
	s_nop 0
	s_add_u32 s100, s66, s92
	s_addc_u32 s101, s67, s93
	global_load_lds_dwordx4 v182, s[100:101]
	s_waitcnt vmcnt(8) lgkmcnt(0)
	s_barrier
	v_mfma_i32_16x16x64_i8 v[96:99], v[100:103], v[216:219], v[96:99]
	v_mfma_i32_16x16x64_i8 v[88:91], v[172:175], v[216:219], v[88:91]
	v_mfma_i32_16x16x64_i8 v[80:83], v[100:103], v[224:227], v[80:83]
	v_mfma_i32_16x16x64_i8 v[72:75], v[172:175], v[224:227], v[72:75]
	v_mfma_i32_16x16x64_i8 v[64:67], v[100:103], v[232:235], v[64:67]
	v_mfma_i32_16x16x64_i8 v[56:59], v[172:175], v[232:235], v[56:59]
	v_mfma_i32_16x16x64_i8 v[48:51], v[100:103], v[240:243], v[48:51]
	v_mfma_i32_16x16x64_i8 v[40:43], v[172:175], v[240:243], v[40:43]
	v_mfma_i32_16x16x64_i8 v[96:99], v[112:115], v[220:223], v[96:99]
	v_mfma_i32_16x16x64_i8 v[88:91], v[188:191], v[220:223], v[88:91]
	v_mfma_i32_16x16x64_i8 v[80:83], v[112:115], v[228:231], v[80:83]
	v_mfma_i32_16x16x64_i8 v[72:75], v[188:191], v[228:231], v[72:75]
	v_mfma_i32_16x16x64_i8 v[64:67], v[112:115], v[236:239], v[64:67]
	v_mfma_i32_16x16x64_i8 v[56:59], v[188:191], v[236:239], v[56:59]
	v_mfma_i32_16x16x64_i8 v[48:51], v[112:115], v[244:247], v[48:51]
	v_mfma_i32_16x16x64_i8 v[40:43], v[188:191], v[244:247], v[40:43]
	v_mfma_i32_16x16x64_i8 v[92:95], v[192:195], v[216:219], v[92:95]
	v_mfma_i32_16x16x64_i8 v[84:87], v[204:207], v[216:219], v[84:87]
	v_mfma_i32_16x16x64_i8 v[76:79], v[192:195], v[224:227], v[76:79]
	v_mfma_i32_16x16x64_i8 v[68:71], v[204:207], v[224:227], v[68:71]
	v_mfma_i32_16x16x64_i8 v[60:63], v[192:195], v[232:235], v[60:63]
	v_mfma_i32_16x16x64_i8 v[52:55], v[204:207], v[232:235], v[52:55]
	v_mfma_i32_16x16x64_i8 v[44:47], v[192:195], v[240:243], v[44:47]
	v_mfma_i32_16x16x64_i8 v[36:39], v[204:207], v[240:243], v[36:39]
	v_mfma_i32_16x16x64_i8 v[92:95], v[200:203], v[220:223], v[92:95]
	v_mfma_i32_16x16x64_i8 v[84:87], v[210:213], v[220:223], v[84:87]
	v_mfma_i32_16x16x64_i8 v[76:79], v[200:203], v[228:231], v[76:79]
	v_mfma_i32_16x16x64_i8 v[68:71], v[210:213], v[228:231], v[68:71]
	v_mfma_i32_16x16x64_i8 v[60:63], v[200:203], v[236:239], v[60:63]
	v_mfma_i32_16x16x64_i8 v[52:55], v[210:213], v[236:239], v[52:55]
	v_mfma_i32_16x16x64_i8 v[44:47], v[200:203], v[244:247], v[44:47]
	v_mfma_i32_16x16x64_i8 v[36:39], v[210:213], v[244:247], v[36:39]
	s_barrier
	s_add_i32 s59, s59, 2
	s_add_u32 s28, s28, 0x10000
	s_addc_u32 s58, s58, 0
	s_add_u32 s12, s12, 0x100
	s_addc_u32 s13, s13, 0
	s_cmp_gt_u32 s59, 29
	s_cbranch_scc0 .LBB0_1070
	s_and_b64 vcc, exec, s[46:47]
	s_cbranch_vccz .LBB0_1073
	s_barrier

.LBB0_1260:
	s_add_u32 s58, s42, 0x10000
	v_mov_b32_e32 v2, 0
	s_addc_u32 s59, s43, 0
	s_mov_b32 s60, -2
	v_mov_b32_e32 v3, v2
	v_mov_b32_e32 v4, v2
	v_mov_b32_e32 v5, v2
	v_mov_b32_e32 v6, v2
	v_mov_b32_e32 v7, v2
	v_mov_b32_e32 v8, v2
	v_mov_b32_e32 v9, v2
	v_mov_b32_e32 v18, v2
	v_mov_b32_e32 v19, v2
	v_mov_b32_e32 v20, v2
	v_mov_b32_e32 v21, v2
	v_mov_b32_e32 v22, v2
	v_mov_b32_e32 v23, v2
	v_mov_b32_e32 v24, v2
	v_mov_b32_e32 v25, v2
	v_mov_b32_e32 v36, v2
	v_mov_b32_e32 v37, v2
	v_mov_b32_e32 v38, v2
	v_mov_b32_e32 v39, v2
	v_mov_b32_e32 v40, v2
	v_mov_b32_e32 v41, v2
	v_mov_b32_e32 v42, v2
	v_mov_b32_e32 v43, v2
	v_mov_b32_e32 v52, v2
	v_mov_b32_e32 v53, v2
	v_mov_b32_e32 v54, v2
	v_mov_b32_e32 v55, v2
	v_mov_b32_e32 v56, v2
	v_mov_b32_e32 v57, v2
	v_mov_b32_e32 v58, v2
	v_mov_b32_e32 v59, v2
	v_mov_b32_e32 v10, v2
	v_mov_b32_e32 v11, v2
	v_mov_b32_e32 v12, v2
	v_mov_b32_e32 v13, v2
	v_mov_b32_e32 v14, v2
	v_mov_b32_e32 v15, v2
	v_mov_b32_e32 v16, v2
	v_mov_b32_e32 v17, v2
	v_mov_b32_e32 v26, v2
	v_mov_b32_e32 v27, v2
	v_mov_b32_e32 v28, v2
	v_mov_b32_e32 v29, v2
	v_mov_b32_e32 v30, v2
	v_mov_b32_e32 v31, v2
	v_mov_b32_e32 v32, v2
	v_mov_b32_e32 v33, v2
	v_mov_b32_e32 v44, v2
	v_mov_b32_e32 v45, v2
	v_mov_b32_e32 v46, v2
	v_mov_b32_e32 v47, v2
	v_mov_b32_e32 v48, v2
	v_mov_b32_e32 v49, v2
	v_mov_b32_e32 v50, v2
	v_mov_b32_e32 v51, v2
	v_mov_b32_e32 v60, v2
	v_mov_b32_e32 v61, v2
	v_mov_b32_e32 v62, v2
	v_mov_b32_e32 v63, v2
	v_mov_b32_e32 v64, v2
	v_mov_b32_e32 v65, v2
	v_mov_b32_e32 v66, v2
	v_mov_b32_e32 v67, v2
	v_mov_b32_e32 v68, v2
	v_mov_b32_e32 v69, v2
	v_mov_b32_e32 v70, v2
	v_mov_b32_e32 v71, v2
	v_mov_b32_e32 v72, v2
	v_mov_b32_e32 v73, v2
	v_mov_b32_e32 v74, v2
	v_mov_b32_e32 v75, v2
	v_mov_b32_e32 v84, v2
	v_mov_b32_e32 v85, v2
	v_mov_b32_e32 v86, v2
	v_mov_b32_e32 v87, v2
	v_mov_b32_e32 v88, v2
	v_mov_b32_e32 v89, v2
	v_mov_b32_e32 v90, v2
	v_mov_b32_e32 v91, v2
	v_mov_b32_e32 v100, v2
	v_mov_b32_e32 v101, v2
	v_mov_b32_e32 v102, v2
	v_mov_b32_e32 v103, v2
	v_mov_b32_e32 v104, v2
	v_mov_b32_e32 v105, v2
	v_mov_b32_e32 v106, v2
	v_mov_b32_e32 v107, v2
	v_mov_b32_e32 v116, v2
	v_mov_b32_e32 v117, v2
	v_mov_b32_e32 v118, v2
	v_mov_b32_e32 v119, v2
	v_mov_b32_e32 v120, v2
	v_mov_b32_e32 v121, v2
	v_mov_b32_e32 v122, v2
	v_mov_b32_e32 v123, v2
	v_mov_b32_e32 v76, v2
	v_mov_b32_e32 v77, v2
	v_mov_b32_e32 v78, v2
	v_mov_b32_e32 v79, v2
	v_mov_b32_e32 v80, v2
	v_mov_b32_e32 v81, v2
	v_mov_b32_e32 v82, v2
	v_mov_b32_e32 v83, v2
	v_mov_b32_e32 v92, v2
	v_mov_b32_e32 v93, v2
	v_mov_b32_e32 v94, v2
	v_mov_b32_e32 v95, v2
	v_mov_b32_e32 v96, v2
	v_mov_b32_e32 v97, v2
	v_mov_b32_e32 v98, v2
	v_mov_b32_e32 v99, v2
	v_mov_b32_e32 v108, v2
	v_mov_b32_e32 v109, v2
	v_mov_b32_e32 v110, v2
	v_mov_b32_e32 v111, v2
	v_mov_b32_e32 v112, v2
	v_mov_b32_e32 v113, v2
	v_mov_b32_e32 v114, v2
	v_mov_b32_e32 v115, v2
	v_mov_b32_e32 v124, v2
	v_mov_b32_e32 v125, v2
	v_mov_b32_e32 v126, v2
	v_mov_b32_e32 v127, v2
	v_mov_b32_e32 v128, v2
	v_mov_b32_e32 v129, v2
	v_mov_b32_e32 v130, v2
	v_mov_b32_e32 v131, v2
	v_add_u32_e32 v188, 0x10000, v186
.LBB0_1261:
	s_add_u32 s42, s22, 0x100
	s_addc_u32 s43, s23, 0
	s_add_i32 s34, 0, 0x10000
	s_cmpk_eq_i32 s60, 0xa8
	s_cselect_b32 s51, s19, s43
	s_cselect_b32 s50, s18, s42
	s_cselect_b32 s49, s21, s59
	s_cselect_b32 s48, s20, s58
	s_add_i32 s35, 0, 0x14000
	ds_read_b128 v[132:135], v188 offset:0
	ds_read_b128 v[136:139], v188 offset:1024
	ds_read_b128 v[140:143], v188 offset:2048
	ds_read_b128 v[144:147], v188 offset:3072
	ds_read_b128 v[148:151], v188 offset:16384
	ds_read_b128 v[152:155], v188 offset:17408
	ds_read_b128 v[168:171], v188 offset:18432
	ds_read_b128 v[172:175], v188 offset:19456
	s_add_i32 m0, s29, 0xc000
	ds_read_b128 v[176:179], v187
	ds_read_b128 v[180:183], v187 offset:1024
	ds_read_b128 v[192:195], v187 offset:2048
	ds_read_b128 v[210:213], v187 offset:3072
	ds_read_b128 v[232:235], v187 offset:4096
	ds_read_b128 v[236:239], v187 offset:5120
	ds_read_b128 v[240:243], v187 offset:6144
	ds_read_b128 v[244:247], v187 offset:7168
	global_load_lds_dwordx4 v164, s[22:23]
	s_add_i32 m0, s29, 0xe000
	s_nop 0
	global_load_lds_dwordx4 v166, s[22:23]
	s_waitcnt vmcnt(8) lgkmcnt(0)
	s_barrier
	v_mfma_f32_16x16x32_bf16 v[128:131], v[132:135], v[176:179], v[128:131]
	v_mfma_f32_16x16x32_bf16 v[124:127], v[140:143], v[176:179], v[124:127]
	v_mfma_f32_16x16x32_bf16 v[112:115], v[132:135], v[192:195], v[112:115]
	v_mfma_f32_16x16x32_bf16 v[108:111], v[140:143], v[192:195], v[108:111]
	v_mfma_f32_16x16x32_bf16 v[96:99], v[132:135], v[232:235], v[96:99]
	v_mfma_f32_16x16x32_bf16 v[92:95], v[140:143], v[232:235], v[92:95]
	v_mfma_f32_16x16x32_bf16 v[80:83], v[132:135], v[240:243], v[80:83]
	v_mfma_f32_16x16x32_bf16 v[76:79], v[140:143], v[240:243], v[76:79]
	v_mfma_f32_16x16x32_bf16 v[128:131], v[136:139], v[180:183], v[128:131]
	v_mfma_f32_16x16x32_bf16 v[124:127], v[144:147], v[180:183], v[124:127]
	v_mfma_f32_16x16x32_bf16 v[112:115], v[136:139], v[210:213], v[112:115]
	v_mfma_f32_16x16x32_bf16 v[108:111], v[144:147], v[210:213], v[108:111]
	v_mfma_f32_16x16x32_bf16 v[96:99], v[136:139], v[236:239], v[96:99]
	v_mfma_f32_16x16x32_bf16 v[92:95], v[144:147], v[236:239], v[92:95]
	v_mfma_f32_16x16x32_bf16 v[80:83], v[136:139], v[244:247], v[80:83]
	v_mfma_f32_16x16x32_bf16 v[76:79], v[144:147], v[244:247], v[76:79]
	v_mfma_f32_16x16x32_bf16 v[120:123], v[148:151], v[176:179], v[120:123]
	v_mfma_f32_16x16x32_bf16 v[116:119], v[168:171], v[176:179], v[116:119]
	v_mfma_f32_16x16x32_bf16 v[104:107], v[148:151], v[192:195], v[104:107]
	v_mfma_f32_16x16x32_bf16 v[100:103], v[168:171], v[192:195], v[100:103]
	v_mfma_f32_16x16x32_bf16 v[88:91], v[148:151], v[232:235], v[88:91]
	v_mfma_f32_16x16x32_bf16 v[84:87], v[168:171], v[232:235], v[84:87]
	v_mfma_f32_16x16x32_bf16 v[72:75], v[148:151], v[240:243], v[72:75]
	v_mfma_f32_16x16x32_bf16 v[68:71], v[168:171], v[240:243], v[68:71]
	v_mfma_f32_16x16x32_bf16 v[120:123], v[152:155], v[180:183], v[120:123]
	v_mfma_f32_16x16x32_bf16 v[116:119], v[172:175], v[180:183], v[116:119]
	v_mfma_f32_16x16x32_bf16 v[104:107], v[152:155], v[210:213], v[104:107]
	v_mfma_f32_16x16x32_bf16 v[100:103], v[172:175], v[210:213], v[100:103]
	v_mfma_f32_16x16x32_bf16 v[88:91], v[152:155], v[236:239], v[88:91]
	v_mfma_f32_16x16x32_bf16 v[84:87], v[172:175], v[236:239], v[84:87]
	v_mfma_f32_16x16x32_bf16 v[72:75], v[152:155], v[244:247], v[72:75]
	v_mfma_f32_16x16x32_bf16 v[68:71], v[172:175], v[244:247], v[68:71]
	s_barrier
	s_add_i32 s22, s34, s0
	s_mov_b32 m0, s22
	ds_read_b128 v[176:179], v187 offset:16384
	ds_read_b128 v[180:183], v187 offset:17408
	ds_read_b128 v[192:195], v187 offset:18432
	ds_read_b128 v[210:213], v187 offset:19456
	ds_read_b128 v[232:235], v187 offset:20480
	ds_read_b128 v[236:239], v187 offset:21504
	ds_read_b128 v[240:243], v187 offset:22528
	ds_read_b128 v[244:247], v187 offset:23552
	global_load_lds_dwordx4 v156, s[48:49]
	s_add_i32 m0, s22, 0x2000
	s_add_u32 s22, s48, 0x4000
	s_addc_u32 s23, s49, 0
	s_add_i32 s34, s35, s0
	global_load_lds_dwordx4 v160, s[48:49]
	s_mov_b32 m0, s34
	s_nop 0
	global_load_lds_dwordx4 v156, s[22:23]
	s_add_i32 m0, s34, 0x2000
	s_nop 0
	global_load_lds_dwordx4 v160, s[22:23]
	s_mov_b32 m0, s29
	s_nop 0
	global_load_lds_dwordx4 v158, s[50:51]
	s_mov_b32 m0, s45
	s_nop 0
	global_load_lds_dwordx4 v162, s[50:51]
	s_waitcnt vmcnt(8) lgkmcnt(0)
	s_barrier
	v_mfma_f32_16x16x32_bf16 v[64:67], v[132:135], v[176:179], v[64:67]
	v_mfma_f32_16x16x32_bf16 v[60:63], v[140:143], v[176:179], v[60:63]
	v_mfma_f32_16x16x32_bf16 v[48:51], v[132:135], v[192:195], v[48:51]
	v_mfma_f32_16x16x32_bf16 v[44:47], v[140:143], v[192:195], v[44:47]
	v_mfma_f32_16x16x32_bf16 v[30:33], v[132:135], v[232:235], v[30:33]
	v_mfma_f32_16x16x32_bf16 v[26:29], v[140:143], v[232:235], v[26:29]
	v_mfma_f32_16x16x32_bf16 v[14:17], v[132:135], v[240:243], v[14:17]
	v_mfma_f32_16x16x32_bf16 v[10:13], v[140:143], v[240:243], v[10:13]
	v_mfma_f32_16x16x32_bf16 v[64:67], v[136:139], v[180:183], v[64:67]
	v_mfma_f32_16x16x32_bf16 v[60:63], v[144:147], v[180:183], v[60:63]
	v_mfma_f32_16x16x32_bf16 v[48:51], v[136:139], v[210:213], v[48:51]
	v_mfma_f32_16x16x32_bf16 v[44:47], v[144:147], v[210:213], v[44:47]
	v_mfma_f32_16x16x32_bf16 v[30:33], v[136:139], v[236:239], v[30:33]
	v_mfma_f32_16x16x32_bf16 v[26:29], v[144:147], v[236:239], v[26:29]
	v_mfma_f32_16x16x32_bf16 v[14:17], v[136:139], v[244:247], v[14:17]
	v_mfma_f32_16x16x32_bf16 v[10:13], v[144:147], v[244:247], v[10:13]
	v_mfma_f32_16x16x32_bf16 v[56:59], v[148:151], v[176:179], v[56:59]
	v_mfma_f32_16x16x32_bf16 v[52:55], v[168:171], v[176:179], v[52:55]
	v_mfma_f32_16x16x32_bf16 v[40:43], v[148:151], v[192:195], v[40:43]
	v_mfma_f32_16x16x32_bf16 v[36:39], v[168:171], v[192:195], v[36:39]
	v_mfma_f32_16x16x32_bf16 v[22:25], v[148:151], v[232:235], v[22:25]
	v_mfma_f32_16x16x32_bf16 v[18:21], v[168:171], v[232:235], v[18:21]
	v_mfma_f32_16x16x32_bf16 v[6:9], v[148:151], v[240:243], v[6:9]
	v_mfma_f32_16x16x32_bf16 v[2:5], v[168:171], v[240:243], v[2:5]
	v_mfma_f32_16x16x32_bf16 v[56:59], v[152:155], v[180:183], v[56:59]
	v_mfma_f32_16x16x32_bf16 v[52:55], v[172:175], v[180:183], v[52:55]
	v_mfma_f32_16x16x32_bf16 v[40:43], v[152:155], v[210:213], v[40:43]
	v_mfma_f32_16x16x32_bf16 v[36:39], v[172:175], v[210:213], v[36:39]
	v_mfma_f32_16x16x32_bf16 v[22:25], v[152:155], v[236:239], v[22:25]
	v_mfma_f32_16x16x32_bf16 v[18:21], v[172:175], v[236:239], v[18:21]
	v_mfma_f32_16x16x32_bf16 v[6:9], v[152:155], v[244:247], v[6:9]
	v_mfma_f32_16x16x32_bf16 v[2:5], v[172:175], v[244:247], v[2:5]
	s_barrier
	s_add_i32 s34, 0, 0x18000
	s_add_i32 s35, 0, 0x1c000
	ds_read_b128 v[132:135], v188 offset:32768
	ds_read_b128 v[136:139], v188 offset:33792
	ds_read_b128 v[140:143], v188 offset:34816
	ds_read_b128 v[144:147], v188 offset:35840
	ds_read_b128 v[148:151], v188 offset:49152
	ds_read_b128 v[152:155], v188 offset:50176
	ds_read_b128 v[168:171], v188 offset:51200
	ds_read_b128 v[172:175], v188 offset:52224
	s_add_u32 s22, s50, 0x2b0000
	s_addc_u32 s23, s51, 0
	s_mov_b32 m0, s82
	ds_read_b128 v[176:179], v187 offset:32768
	ds_read_b128 v[180:183], v187 offset:33792
	ds_read_b128 v[192:195], v187 offset:34816
	ds_read_b128 v[210:213], v187 offset:35840
	ds_read_b128 v[232:235], v187 offset:36864
	ds_read_b128 v[236:239], v187 offset:37888
	ds_read_b128 v[240:243], v187 offset:38912
	ds_read_b128 v[244:247], v187 offset:39936
	global_load_lds_dwordx4 v158, s[22:23]
	s_mov_b32 m0, s90
	s_nop 0
	global_load_lds_dwordx4 v162, s[22:23]
	s_waitcnt vmcnt(8) lgkmcnt(0)
	s_barrier
	v_mfma_f32_16x16x32_bf16 v[128:131], v[132:135], v[176:179], v[128:131]
	v_mfma_f32_16x16x32_bf16 v[124:127], v[140:143], v[176:179], v[124:127]
	v_mfma_f32_16x16x32_bf16 v[112:115], v[132:135], v[192:195], v[112:115]
	v_mfma_f32_16x16x32_bf16 v[108:111], v[140:143], v[192:195], v[108:111]
	v_mfma_f32_16x16x32_bf16 v[96:99], v[132:135], v[232:235], v[96:99]
	v_mfma_f32_16x16x32_bf16 v[92:95], v[140:143], v[232:235], v[92:95]
	v_mfma_f32_16x16x32_bf16 v[80:83], v[132:135], v[240:243], v[80:83]
	v_mfma_f32_16x16x32_bf16 v[76:79], v[140:143], v[240:243], v[76:79]
	v_mfma_f32_16x16x32_bf16 v[128:131], v[136:139], v[180:183], v[128:131]
	v_mfma_f32_16x16x32_bf16 v[124:127], v[144:147], v[180:183], v[124:127]
	v_mfma_f32_16x16x32_bf16 v[112:115], v[136:139], v[210:213], v[112:115]
	v_mfma_f32_16x16x32_bf16 v[108:111], v[144:147], v[210:213], v[108:111]
	v_mfma_f32_16x16x32_bf16 v[96:99], v[136:139], v[236:239], v[96:99]
	v_mfma_f32_16x16x32_bf16 v[92:95], v[144:147], v[236:239], v[92:95]
	v_mfma_f32_16x16x32_bf16 v[80:83], v[136:139], v[244:247], v[80:83]
	v_mfma_f32_16x16x32_bf16 v[76:79], v[144:147], v[244:247], v[76:79]
	v_mfma_f32_16x16x32_bf16 v[120:123], v[148:151], v[176:179], v[120:123]
	v_mfma_f32_16x16x32_bf16 v[116:119], v[168:171], v[176:179], v[116:119]
	v_mfma_f32_16x16x32_bf16 v[104:107], v[148:151], v[192:195], v[104:107]
	v_mfma_f32_16x16x32_bf16 v[100:103], v[168:171], v[192:195], v[100:103]
	v_mfma_f32_16x16x32_bf16 v[88:91], v[148:151], v[232:235], v[88:91]
	v_mfma_f32_16x16x32_bf16 v[84:87], v[168:171], v[232:235], v[84:87]
	v_mfma_f32_16x16x32_bf16 v[72:75], v[148:151], v[240:243], v[72:75]
	v_mfma_f32_16x16x32_bf16 v[68:71], v[168:171], v[240:243], v[68:71]
	v_mfma_f32_16x16x32_bf16 v[120:123], v[152:155], v[180:183], v[120:123]
	v_mfma_f32_16x16x32_bf16 v[116:119], v[172:175], v[180:183], v[116:119]
	v_mfma_f32_16x16x32_bf16 v[104:107], v[152:155], v[210:213], v[104:107]
	v_mfma_f32_16x16x32_bf16 v[100:103], v[172:175], v[210:213], v[100:103]
	v_mfma_f32_16x16x32_bf16 v[88:91], v[152:155], v[236:239], v[88:91]
	v_mfma_f32_16x16x32_bf16 v[84:87], v[172:175], v[236:239], v[84:87]
	v_mfma_f32_16x16x32_bf16 v[72:75], v[152:155], v[244:247], v[72:75]
	v_mfma_f32_16x16x32_bf16 v[68:71], v[172:175], v[244:247], v[68:71]
	s_barrier
	s_add_u32 s22, s48, 0x8000
	s_addc_u32 s23, s49, 0
	s_add_i32 s34, s34, s0
	s_mov_b32 m0, s34
	ds_read_b128 v[176:179], v187 offset:49152
	ds_read_b128 v[180:183], v187 offset:50176
	ds_read_b128 v[192:195], v187 offset:51200
	ds_read_b128 v[210:213], v187 offset:52224
	ds_read_b128 v[232:235], v187 offset:53248
	ds_read_b128 v[236:239], v187 offset:54272
	ds_read_b128 v[240:243], v187 offset:55296
	ds_read_b128 v[244:247], v187 offset:56320
	global_load_lds_dwordx4 v156, s[22:23]
	s_add_i32 m0, s34, 0x2000
	v_lshl_add_u64 v[250:251], s[22:23], 0, v[160:161]
	s_add_u32 s22, s48, 0xc000
	s_addc_u32 s23, s49, 0
	s_add_i32 s34, s35, s0
	global_load_lds_dwordx4 v[250:251], off
	s_mov_b32 m0, s34
	s_nop 0
	global_load_lds_dwordx4 v156, s[22:23]
	s_add_i32 m0, s34, 0x2000
	s_nop 0
	global_load_lds_dwordx4 v160, s[22:23]
	s_mov_b32 m0, s91
	s_nop 0
	s_add_u32 s100, s50, s92
	s_addc_u32 s101, s51, s93
	global_load_lds_dwordx4 v158, s[100:101]
	s_mov_b32 m0, s30
	s_nop 0
	s_add_u32 s100, s50, s92
	s_addc_u32 s101, s51, s93
	global_load_lds_dwordx4 v162, s[100:101]
	s_waitcnt vmcnt(8) lgkmcnt(0)
	s_barrier
	v_mfma_f32_16x16x32_bf16 v[64:67], v[132:135], v[176:179], v[64:67]
	v_mfma_f32_16x16x32_bf16 v[60:63], v[140:143], v[176:179], v[60:63]
	v_mfma_f32_16x16x32_bf16 v[48:51], v[132:135], v[192:195], v[48:51]
	v_mfma_f32_16x16x32_bf16 v[44:47], v[140:143], v[192:195], v[44:47]
	v_mfma_f32_16x16x32_bf16 v[30:33], v[132:135], v[232:235], v[30:33]
	v_mfma_f32_16x16x32_bf16 v[26:29], v[140:143], v[232:235], v[26:29]
	v_mfma_f32_16x16x32_bf16 v[14:17], v[132:135], v[240:243], v[14:17]
	v_mfma_f32_16x16x32_bf16 v[10:13], v[140:143], v[240:243], v[10:13]
	v_mfma_f32_16x16x32_bf16 v[64:67], v[136:139], v[180:183], v[64:67]
	v_mfma_f32_16x16x32_bf16 v[60:63], v[144:147], v[180:183], v[60:63]
	v_mfma_f32_16x16x32_bf16 v[48:51], v[136:139], v[210:213], v[48:51]
	v_mfma_f32_16x16x32_bf16 v[44:47], v[144:147], v[210:213], v[44:47]
	v_mfma_f32_16x16x32_bf16 v[30:33], v[136:139], v[236:239], v[30:33]
	v_mfma_f32_16x16x32_bf16 v[26:29], v[144:147], v[236:239], v[26:29]
	v_mfma_f32_16x16x32_bf16 v[14:17], v[136:139], v[244:247], v[14:17]
	v_mfma_f32_16x16x32_bf16 v[10:13], v[144:147], v[244:247], v[10:13]
	v_mfma_f32_16x16x32_bf16 v[56:59], v[148:151], v[176:179], v[56:59]
	v_mfma_f32_16x16x32_bf16 v[52:55], v[168:171], v[176:179], v[52:55]
	v_mfma_f32_16x16x32_bf16 v[40:43], v[148:151], v[192:195], v[40:43]
	v_mfma_f32_16x16x32_bf16 v[36:39], v[168:171], v[192:195], v[36:39]
	v_mfma_f32_16x16x32_bf16 v[22:25], v[148:151], v[232:235], v[22:25]
	v_mfma_f32_16x16x32_bf16 v[18:21], v[168:171], v[232:235], v[18:21]
	v_mfma_f32_16x16x32_bf16 v[6:9], v[148:151], v[240:243], v[6:9]
	v_mfma_f32_16x16x32_bf16 v[2:5], v[168:171], v[240:243], v[2:5]
	v_mfma_f32_16x16x32_bf16 v[56:59], v[152:155], v[180:183], v[56:59]
	v_mfma_f32_16x16x32_bf16 v[52:55], v[172:175], v[180:183], v[52:55]
	v_mfma_f32_16x16x32_bf16 v[40:43], v[152:155], v[210:213], v[40:43]
	v_mfma_f32_16x16x32_bf16 v[36:39], v[172:175], v[210:213], v[36:39]
	v_mfma_f32_16x16x32_bf16 v[22:25], v[152:155], v[236:239], v[22:25]
	v_mfma_f32_16x16x32_bf16 v[18:21], v[172:175], v[236:239], v[18:21]
	v_mfma_f32_16x16x32_bf16 v[6:9], v[152:155], v[244:247], v[6:9]
	v_mfma_f32_16x16x32_bf16 v[2:5], v[172:175], v[244:247], v[2:5]
	s_barrier
	s_add_i32 s60, s60, 2
	s_add_u32 s58, s58, 0x10000
	s_addc_u32 s59, s59, 0
	s_cmpk_gt_u32 s60, 0xa9
	s_mov_b64 s[22:23], s[42:43]
	s_cbranch_scc0 .LBB0_1261
	s_and_b64 vcc, exec, s[46:47]
	s_cbranch_vccz .LBB0_1264
	s_barrier
